# hand-written forget-gate tail: gate weights in registers, packed-f32 dot products over raw rows with the rms/shift terms folded in after the lane reduction, permlane-swap + DPP transposing reduction,
# speedup vs baseline: 1.0139x; 1.0083x over previous
; __device__ __forceinline__ void fg_tail(const Args& a, int l, LAS unsigned char* lds, const int tid) {
;     ...
;     LAS f32x4* wl = (LAS f32x4*)lds;
;     {
;         const f32x4* wsrc = (const f32x4*)((const float*)(ws + WS_WFGT) + (size_t)l * 8192);
; #pragma unroll
;         for (int i = 0; i < 4; ++i) { const int idx = tid + 512 * i, j = idx >> 8, k4 = idx & 255, ln = k4 >> 2, q = k4 & 3; wl[(j * 4 + q) * 64 + ln] = wsrc[idx]; }
;     }
;     __syncthreads();
;     const bf16_t* H = (const bf16_t*)(ws + WS_H); const float* rowss = (const float*)(ws + WS_ROWSS) + (size_t)(2 * l) * MT * 4;
;     const float* mod = (const float*)(ws + WS_MOD) + (size_t)l * 8 * MODW; float* logf = (float*)(ws + WS_LOGF);
;     const float bfv = a.in[7][l * 8 + (lane >> 3)];
;     for (int chunk = blockIdx.x * 8 + wid; chunk * 8 < MT; chunk += gridDim.x * 8) {
;         const int rowc = chunk * 8, b = rowc >> 11;
;         f32x4 sh[4];
; #pragma unroll
;         for (int q = 0; q < 4; ++q) sh[q] = *(const f32x4*)(mod + (size_t)b * MODW + 16 * lane + 4 * q);
; #pragma unroll 1
;         for (int jb = 0; jb < 8; jb += 4) {
;             f32x4 rs4v[4]; u32x4 w0v[4], w1v[4];
; #pragma unroll
;             for (int j = 0; j < 4; ++j) { const int row = rowc + jb + j; rs4v[j] = *(const f32x4*)(rowss + (size_t)row * 4); w0v[j] = *(const u32x4*)(H + (size_t)row * DM + 16 * lane); w1v[j] = *(const u32x4*)(H + (size_t)row * DM + 16 * lane + 8); }
; #pragma unroll
;             for (int j = 0; j < 4; ++j) {
;                 const int row = rowc + jb + j;
;                 const f32x4 rs4 = rs4v[j]; const u32x4 w0 = w0v[j], w1 = w1v[j];
;                 const float r = 1.0f / sqrtf(((rs4[0] + rs4[1]) + (rs4[2] + rs4[3])) * (1.0f / 1024.0f) + EPS);
;                 float h[16];
; #pragma unroll
;                 for (int i = 0; i < 4; ++i) { h[2 * i] = __uint_as_float(w0[i] << 16); h[2 * i + 1] = __uint_as_float(w0[i] & 0xffff0000u); h[8 + 2 * i] = __uint_as_float(w1[i] << 16); h[8 + 2 * i + 1] = __uint_as_float(w1[i] & 0xffff0000u); }
; #pragma unroll
;                 for (int q = 0; q < 4; ++q) { h[4 * q] = h[4 * q] * r + sh[q][0]; h[4 * q + 1] = h[4 * q + 1] * r + sh[q][1]; h[4 * q + 2] = h[4 * q + 2] * r + sh[q][2]; h[4 * q + 3] = h[4 * q + 3] * r + sh[q][3]; }
;                 float d8[8];
; #pragma unroll
;                 for (int j8 = 0; j8 < 8; ++j8) { float acc = 0.f;
.LBB0_480:
	v_readlane_b32 s0, v252, 24
	v_lshlrev_b32_e32 v0, 10, v188
	s_waitcnt vmcnt(0)
	v_lshlrev_b32_e32 v2, 2, v188
	v_ashrrev_i32_e32 v189, 31, v188
	v_readlane_b32 s1, v252, 25
	v_and_b32_e32 v0, 0xc00, v0
	v_and_b32_e32 v2, 0x3f0, v2
	s_waitcnt lgkmcnt(0)
	v_lshl_add_u64 v[190:191], v[188:189], 4, s[0:1]
	v_add3_u32 v0, 0, v0, v2
	v_and_b32_e32 v18, 0xfffff00, v188
	v_lshl_add_u32 v209, v18, 4, v0
	v_add_u32_e32 v18, 0x200, v188
	v_and_b32_e32 v18, 0xfffff00, v18
	v_lshl_add_u32 v210, v18, 4, v0
	v_add_u32_e32 v18, 0x400, v188
	v_and_b32_e32 v18, 0xfffff00, v18
	v_lshl_add_u32 v211, v18, 4, v0
	v_add_u32_e32 v18, 0x600, v188
	v_and_b32_e32 v18, 0xfffff00, v18
	v_lshl_add_u32 v213, v18, 4, v0
	v_readlane_b32 s0, v252, 26
	v_ashrrev_i32_e32 v0, 6, v188
	v_mov_b32_e32 v212, v248
	v_and_b32_e32 v208, 63, v188
	v_bfe_u32 v2, v188, 3, 3
	v_or_b32_e32 v2, s0, v2
	v_readlane_b32 s0, v249, 3
	v_ashrrev_i32_e32 v3, 31, v2
	v_lshl_add_u64 v[192:193], v[2:3], 2, s[74:75]
	v_add_u32_e32 v189, s0, v0
	s_movk_i32 s0, 0x800
	v_cmp_gt_i32_e64 s[0:1], s0, v189
	v_readlane_b32 s2, v252, 32
	v_readlane_b32 s3, v252, 33
	v_readlane_b32 s4, v249, 61
	v_readlane_b32 s5, v249, 62
	s_mov_b32 s30, 0xcccccccc
	s_mov_b32 s31, 0xcccccccc
	s_mov_b32 s40, 0xaaaaaaaa
	s_mov_b32 s41, 0xaaaaaaaa
	v_lshlrev_b32_e32 v184, 14, v189
	v_lshl_add_u32 v184, v208, 5, v184
	v_lshrrev_b32_e32 v215, 8, v189
	v_mul_u32_u24_e32 v215, 0x6000, v215
	v_lshl_add_u32 v215, v208, 6, v215
	v_and_b32_e32 v216, 7, v208
	v_lshlrev_b32_e32 v217, 7, v189
	v_lshl_add_u32 v217, v216, 4, v217
	v_lshlrev_b32_e32 v246, 8, v189
	v_lshl_add_u32 v246, v216, 5, v246
	v_lshrrev_b32_e32 v216, 3, v208
	v_lshl_add_u32 v246, v216, 2, v246
	s_and_saveexec_b64 s[38:39], s[0:1]
	global_load_dword v214, v[192:193], off
	global_load_dwordx4 v[130:133], v215, s[2:3]
	global_load_dwordx4 v[134:137], v215, s[2:3] offset:16
	global_load_dwordx4 v[138:141], v215, s[2:3] offset:32
	global_load_dwordx4 v[142:145], v215, s[2:3] offset:48
	global_load_dwordx4 v[178:181], v217, s[34:35]
	global_load_dwordx4 v[146:149], v184, s[94:95]
	global_load_dwordx4 v[150:153], v184, s[94:95] offset:16
	global_load_dwordx4 v[154:157], v184, s[94:95] offset:2048
	global_load_dwordx4 v[158:161], v184, s[94:95] offset:2064
	v_add_u32_e32 v184, 0x1000, v184
	global_load_dwordx4 v[162:165], v184, s[94:95]
	global_load_dwordx4 v[166:169], v184, s[94:95] offset:16
	global_load_dwordx4 v[170:173], v184, s[94:95] offset:2048
	global_load_dwordx4 v[174:177], v184, s[94:95] offset:2064
	v_add_u32_e32 v184, 0x1000, v184
	s_or_b64 exec, exec, s[38:39]
	s_mov_b64 s[6:7], 0x2000
	v_lshl_add_u64 v[18:19], v[190:191], 0, s[6:7]
	s_mov_b64 s[6:7], 0x4000
	v_lshl_add_u64 v[20:21], v[190:191], 0, s[6:7]
	s_mov_b64 s[6:7], 0x6000
	v_lshl_add_u64 v[22:23], v[190:191], 0, s[6:7]
	global_load_dwordx4 v[2:5], v[190:191], off
	global_load_dwordx4 v[6:9], v[18:19], off
	global_load_dwordx4 v[10:13], v[20:21], off
	global_load_dwordx4 v[14:17], v[22:23], off
	s_waitcnt vmcnt(0)
	ds_write_b128 v209, v[2:5]
	ds_write_b128 v210, v[6:9]
	ds_write_b128 v211, v[10:13]
	ds_write_b128 v213, v[14:17]
	s_waitcnt lgkmcnt(0)
	s_barrier
	s_and_saveexec_b64 s[38:39], s[0:1]
	s_cbranch_execz .LBB0_493
	v_lshl_add_u32 v0, v208, 4, 0
	ds_read_b128 v[2:5], v0
	ds_read_b128 v[6:9], v0 offset:1024
	ds_read_b128 v[10:13], v0 offset:2048
	ds_read_b128 v[14:17], v0 offset:3072
	ds_read_b128 v[18:21], v0 offset:4096
	ds_read_b128 v[22:25], v0 offset:5120
	ds_read_b128 v[26:29], v0 offset:6144
	ds_read_b128 v[30:33], v0 offset:7168
	ds_read_b128 v[34:37], v0 offset:8192
	ds_read_b128 v[38:41], v0 offset:9216
	ds_read_b128 v[42:45], v0 offset:10240
	ds_read_b128 v[46:49], v0 offset:11264
	ds_read_b128 v[50:53], v0 offset:12288
	ds_read_b128 v[54:57], v0 offset:13312
	ds_read_b128 v[58:61], v0 offset:14336
	ds_read_b128 v[62:65], v0 offset:15360
	ds_read_b128 v[66:69], v0 offset:16384
	ds_read_b128 v[70:73], v0 offset:17408
	ds_read_b128 v[74:77], v0 offset:18432
	ds_read_b128 v[78:81], v0 offset:19456
	ds_read_b128 v[82:85], v0 offset:20480
	ds_read_b128 v[86:89], v0 offset:21504
	ds_read_b128 v[90:93], v0 offset:22528
	ds_read_b128 v[94:97], v0 offset:23552
	ds_read_b128 v[98:101], v0 offset:24576
	ds_read_b128 v[102:105], v0 offset:25600
	ds_read_b128 v[106:109], v0 offset:26624
	ds_read_b128 v[110:113], v0 offset:27648
	ds_read_b128 v[114:117], v0 offset:28672
	ds_read_b128 v[118:121], v0 offset:29696
	ds_read_b128 v[122:125], v0 offset:30720
	ds_read_b128 v[126:129], v0 offset:31744
	v_mov_b32_e32 v0, v189
; __device__ __forceinline__ void fg_tail(const Args& a, int l, LAS unsigned char* lds, const int tid) {
;     ...
;                 const int row = rowc + jb + j;
;                 const f32x4 rs4 = rs4v[j]; const u32x4 w0 = w0v[j], w1 = w1v[j];
;                 const float r = 1.0f / sqrtf(((rs4[0] + rs4[1]) + (rs4[2] + rs4[3])) * (1.0f / 1024.0f) + EPS);
;                 float h[16];
; #pragma unroll
;                 for (int i = 0; i < 4; ++i) { h[2 * i] = __uint_as_float(w0[i] << 16); h[2 * i + 1] = __uint_as_float(w0[i] & 0xffff0000u); h[8 + 2 * i] = __uint_as_float(w1[i] << 16); h[8 + 2 * i + 1] = __uint_as_float(w1[i] & 0xffff0000u); }
; #pragma unroll
;                 for (int q = 0; q < 4; ++q) { h[4 * q] = h[4 * q] * r + sh[q][0]; h[4 * q + 1] = h[4 * q + 1] * r + sh[q][1]; h[4 * q + 2] = h[4 * q + 2] * r + sh[q][2]; h[4 * q + 3] = h[4 * q + 3] * r + sh[q][3]; }
;                 float d8[8];
; #pragma unroll
;                 for (int j8 = 0; j8 < 8; ++j8) { float acc = 0.f;
; #pragma unroll
;                     for (int q = 0; q < 4; ++q) { const f32x4 w = wl[(j8 * 4 + q) * 64 + lane]; acc += (h[4 * q] * w[0] + h[4 * q + 1] * w[1]) + (h[4 * q + 2] * w[2] + h[4 * q + 3] * w[3]); }
;                     d8[j8] = acc; }
;                 const float tot = reduce8(d8, lane);
.Lfg_loop:
	s_waitcnt vmcnt(0)
	v_add_f32_e32 v215, v178, v179
	v_add_f32_e32 v216, v180, v181
	v_add_f32_e32 v215, v215, v216
	v_fmamk_f32 v215, v215, 0x3a800000, v225
	v_mul_f32_e32 v216, 0x4f800000, v215
	v_cmp_gt_f32_e32 vcc, s16, v215
	s_nop 1
	v_cndmask_b32_e32 v215, v215, v216, vcc
	v_sqrt_f32_e32 v216, v215
	s_nop 0
	v_add_u32_e32 v217, -1, v216
	v_add_u32_e32 v218, 1, v216
	v_fma_f32 v228, -v217, v216, v215
	v_fma_f32 v187, -v218, v216, v215
	v_cmp_ge_f32_e64 s[10:11], 0, v228
	s_nop 1
	v_cndmask_b32_e64 v241, v216, v217, s[10:11]
	v_cmp_lt_f32_e64 s[10:11], 0, v187
	s_nop 1
	v_cndmask_b32_e64 v187, v241, v218, s[10:11]
	v_mul_f32_e32 v241, 0x37800000, v187
	v_cndmask_b32_e32 v187, v187, v241, vcc
	v_cmp_class_f32_e32 vcc, v215, v226
	s_nop 1
	v_cndmask_b32_e32 v187, v187, v215, vcc
	v_div_scale_f32 v241, s[10:11], v187, v187, 1.0
	v_rcp_f32_e32 v215, v241
	v_div_scale_f32 v218, vcc, 1.0, v187, 1.0
	v_fma_f32 v216, -v241, v215, 1.0
	v_fmac_f32_e32 v215, v216, v215
	v_mul_f32_e32 v216, v218, v215
	v_fma_f32 v228, -v241, v216, v218
	v_fmac_f32_e32 v216, v228, v215
	v_fma_f32 v241, -v241, v216, v218
	v_div_fmas_f32 v241, v241, v215, v216
	v_div_fixup_f32 v247, v241, v187, 1.0
	s_waitcnt lgkmcnt(0)
	v_pk_mul_f32 v[194:195], v[130:131], v[2:3]
	v_pk_mul_f32 v[196:197], v[130:131], v[18:19]
	v_pk_mul_f32 v[198:199], v[130:131], v[34:35]
	v_pk_mul_f32 v[200:201], v[130:131], v[50:51]
	v_pk_mul_f32 v[202:203], v[130:131], v[66:67]
	v_pk_mul_f32 v[204:205], v[130:131], v[82:83]
	v_pk_mul_f32 v[206:207], v[130:131], v[98:99]
	v_pk_mul_f32 v[182:183], v[130:131], v[114:115]
	v_pk_fma_f32 v[194:195], v[132:133], v[4:5], v[194:195]
	v_pk_fma_f32 v[196:197], v[132:133], v[20:21], v[196:197]
	v_pk_fma_f32 v[198:199], v[132:133], v[36:37], v[198:199]
	v_pk_fma_f32 v[200:201], v[132:133], v[52:53], v[200:201]
	v_pk_fma_f32 v[202:203], v[132:133], v[68:69], v[202:203]
	v_pk_fma_f32 v[204:205], v[132:133], v[84:85], v[204:205]
	v_pk_fma_f32 v[206:207], v[132:133], v[100:101], v[206:207]
	v_pk_fma_f32 v[182:183], v[132:133], v[116:117], v[182:183]
	v_pk_fma_f32 v[194:195], v[134:135], v[6:7], v[194:195]
	v_pk_fma_f32 v[196:197], v[134:135], v[22:23], v[196:197]
	v_pk_fma_f32 v[198:199], v[134:135], v[38:39], v[198:199]
	v_pk_fma_f32 v[200:201], v[134:135], v[54:55], v[200:201]
	v_pk_fma_f32 v[202:203], v[134:135], v[70:71], v[202:203]
	v_pk_fma_f32 v[204:205], v[134:135], v[86:87], v[204:205]
	v_pk_fma_f32 v[206:207], v[134:135], v[102:103], v[206:207]
	v_pk_fma_f32 v[182:183], v[134:135], v[118:119], v[182:183]
	v_pk_fma_f32 v[194:195], v[136:137], v[8:9], v[194:195]
	v_pk_fma_f32 v[196:197], v[136:137], v[24:25], v[196:197]
	v_pk_fma_f32 v[198:199], v[136:137], v[40:41], v[198:199]
	v_pk_fma_f32 v[200:201], v[136:137], v[56:57], v[200:201]
	v_pk_fma_f32 v[202:203], v[136:137], v[72:73], v[202:203]
	v_pk_fma_f32 v[204:205], v[136:137], v[88:89], v[204:205]
	v_pk_fma_f32 v[206:207], v[136:137], v[104:105], v[206:207]
	v_pk_fma_f32 v[182:183], v[136:137], v[120:121], v[182:183]
	v_pk_fma_f32 v[194:195], v[138:139], v[10:11], v[194:195]
	v_pk_fma_f32 v[196:197], v[138:139], v[26:27], v[196:197]
	v_pk_fma_f32 v[198:199], v[138:139], v[42:43], v[198:199]
	v_pk_fma_f32 v[200:201], v[138:139], v[58:59], v[200:201]
	v_pk_fma_f32 v[202:203], v[138:139], v[74:75], v[202:203]
	v_pk_fma_f32 v[204:205], v[138:139], v[90:91], v[204:205]
	v_pk_fma_f32 v[206:207], v[138:139], v[106:107], v[206:207]
	v_pk_fma_f32 v[182:183], v[138:139], v[122:123], v[182:183]
	v_pk_fma_f32 v[194:195], v[140:141], v[12:13], v[194:195]
	v_pk_fma_f32 v[196:197], v[140:141], v[28:29], v[196:197]
	v_pk_fma_f32 v[198:199], v[140:141], v[44:45], v[198:199]
	v_pk_fma_f32 v[200:201], v[140:141], v[60:61], v[200:201]
	v_pk_fma_f32 v[202:203], v[140:141], v[76:77], v[202:203]
	v_pk_fma_f32 v[204:205], v[140:141], v[92:93], v[204:205]
	v_pk_fma_f32 v[206:207], v[140:141], v[108:109], v[206:207]
	v_pk_fma_f32 v[182:183], v[140:141], v[124:125], v[182:183]
	v_pk_fma_f32 v[194:195], v[142:143], v[14:15], v[194:195]
	v_pk_fma_f32 v[196:197], v[142:143], v[30:31], v[196:197]
	v_pk_fma_f32 v[198:199], v[142:143], v[46:47], v[198:199]
	v_pk_fma_f32 v[200:201], v[142:143], v[62:63], v[200:201]
	v_pk_fma_f32 v[202:203], v[142:143], v[78:79], v[202:203]
	v_pk_fma_f32 v[204:205], v[142:143], v[94:95], v[204:205]
	v_pk_fma_f32 v[206:207], v[142:143], v[110:111], v[206:207]
	v_pk_fma_f32 v[182:183], v[142:143], v[126:127], v[182:183]
	v_pk_fma_f32 v[194:195], v[144:145], v[16:17], v[194:195]
	v_pk_fma_f32 v[196:197], v[144:145], v[32:33], v[196:197]
	v_pk_fma_f32 v[198:199], v[144:145], v[48:49], v[198:199]
	v_pk_fma_f32 v[200:201], v[144:145], v[64:65], v[200:201]
	v_pk_fma_f32 v[202:203], v[144:145], v[80:81], v[202:203]
	v_pk_fma_f32 v[204:205], v[144:145], v[96:97], v[204:205]
	v_pk_fma_f32 v[206:207], v[144:145], v[112:113], v[206:207]
	v_pk_fma_f32 v[182:183], v[144:145], v[128:129], v[182:183]
	v_add_f32_e32 v194, v194, v195
	v_add_f32_e32 v196, v196, v197
	v_add_f32_e32 v198, v198, v199
	v_add_f32_e32 v200, v200, v201
	v_add_f32_e32 v202, v202, v203
	v_add_f32_e32 v204, v204, v205
	v_add_f32_e32 v206, v206, v207
	v_add_f32_e32 v182, v182, v183
	s_nop 1
	v_permlane32_swap_b32_e32 v194, v202
	v_permlane32_swap_b32_e32 v196, v204
	v_permlane32_swap_b32_e32 v198, v206
	v_permlane32_swap_b32_e32 v200, v182
	v_add_f32_e32 v194, v194, v202
	v_add_f32_e32 v196, v196, v204
	v_add_f32_e32 v198, v198, v206
	v_add_f32_e32 v200, v200, v182
	s_nop 1
	v_permlane16_swap_b32_e32 v194, v198
	v_permlane16_swap_b32_e32 v196, v200
	v_add_f32_e32 v194, v194, v198
	v_add_f32_e32 v196, v196, v200
	s_nop 1
; __device__ __forceinline__ void fg_tail(const Args& a, int l, LAS unsigned char* lds, const int tid) {
;     ...
;             for (int j = 0; j < 4; ++j) { const int row = rowc + jb + j; rs4v[j] = *(const f32x4*)(rowss + (size_t)row * 4); w0v[j] = *(const u32x4*)(H + (size_t)row * DM + 16 * lane); w1v[j] = *(const u32x4*)(H + (size_t)row * DM + 16 * lane + 8); }
; #pragma unroll
;             for (int j = 0; j < 4; ++j) {
;                 const int row = rowc + jb + j;
;                 const f32x4 rs4 = rs4v[j]; const u32x4 w0 = w0v[j], w1 = w1v[j];
;                 const float r = 1.0f / sqrtf(((rs4[0] + rs4[1]) + (rs4[2] + rs4[3])) * (1.0f / 1024.0f) + EPS);
;                 float h[16];
; #pragma unroll
;                 for (int i = 0; i < 4; ++i) { h[2 * i] = __uint_as_float(w0[i] << 16); h[2 * i + 1] = __uint_as_float(w0[i] & 0xffff0000u); h[8 + 2 * i] = __uint_as_float(w1[i] << 16); h[8 + 2 * i + 1] = __uint_as_float(w1[i] & 0xffff0000u); }
; #pragma unroll
;                 for (int q = 0; q < 4; ++q) { h[4 * q] = h[4 * q] * r + sh[q][0]; h[4 * q + 1] = h[4 * q + 1] * r + sh[q][1]; h[4 * q + 2] = h[4 * q + 2] * r + sh[q][2]; h[4 * q + 3] = h[4 * q + 3] * r + sh[q][3]; }
;                 float d8[8];
; #pragma unroll
;                 for (int j8 = 0; j8 < 8; ++j8) { float acc = 0.f;
; #pragma unroll
;                     for (int q = 0; q < 4; ++q) { const f32x4 w = wl[(j8 * 4 + q) * 64 + lane]; acc += (h[4 * q] * w[0] + h[4 * q + 1] * w[1]) + (h[4 * q + 2] * w[2] + h[4 * q + 3] * w[3]); }
;                     d8[j8] = acc; }
;                 const float tot = reduce8(d8, lane);
	v_add_f32_dpp v248, v194, v194 row_ror:8 row_mask:0xf bank_mask:0x3
	v_add_f32_dpp v248, v196, v196 row_ror:8 row_mask:0xf bank_mask:0xc
	s_nop 1
	v_add_f32_dpp v248, v248, v248 quad_perm:[1,0,3,2] row_mask:0xf bank_mask:0xf
	s_nop 1
	v_add_f32_dpp v248, v248, v248 quad_perm:[2,3,0,1] row_mask:0xf bank_mask:0xf
	s_nop 1
	v_add_f32_dpp v248, v248, v248 row_half_mirror row_mask:0xf bank_mask:0xf
	v_add_f32_e32 v248, v248, v214
	v_lshlrev_b32_e32 v130, 16, v146
	v_and_b32_e32 v131, 0xffff0000, v146
	v_lshlrev_b32_e32 v132, 16, v147
	v_and_b32_e32 v133, 0xffff0000, v147
	v_lshlrev_b32_e32 v134, 16, v148
	v_and_b32_e32 v135, 0xffff0000, v148
	v_lshlrev_b32_e32 v136, 16, v149
	v_and_b32_e32 v137, 0xffff0000, v149
	v_lshlrev_b32_e32 v138, 16, v150
	v_and_b32_e32 v139, 0xffff0000, v150
	v_lshlrev_b32_e32 v140, 16, v151
	v_and_b32_e32 v141, 0xffff0000, v151
	v_lshlrev_b32_e32 v142, 16, v152
	v_and_b32_e32 v143, 0xffff0000, v152
	v_lshlrev_b32_e32 v144, 16, v153
	v_and_b32_e32 v145, 0xffff0000, v153
	global_load_dwordx4 v[146:149], v184, s[94:95]
	global_load_dwordx4 v[150:153], v184, s[94:95] offset:16
	v_pk_mul_f32 v[194:195], v[130:131], v[2:3]
	v_pk_mul_f32 v[196:197], v[130:131], v[18:19]
	v_pk_mul_f32 v[198:199], v[130:131], v[34:35]
	v_pk_mul_f32 v[200:201], v[130:131], v[50:51]
	v_pk_mul_f32 v[202:203], v[130:131], v[66:67]
	v_pk_mul_f32 v[204:205], v[130:131], v[82:83]
	v_pk_mul_f32 v[206:207], v[130:131], v[98:99]
	v_pk_mul_f32 v[182:183], v[130:131], v[114:115]
	v_pk_fma_f32 v[194:195], v[132:133], v[4:5], v[194:195]
	v_pk_fma_f32 v[196:197], v[132:133], v[20:21], v[196:197]
	v_pk_fma_f32 v[198:199], v[132:133], v[36:37], v[198:199]
	v_pk_fma_f32 v[200:201], v[132:133], v[52:53], v[200:201]
	v_pk_fma_f32 v[202:203], v[132:133], v[68:69], v[202:203]
	v_pk_fma_f32 v[204:205], v[132:133], v[84:85], v[204:205]
	v_pk_fma_f32 v[206:207], v[132:133], v[100:101], v[206:207]
	v_pk_fma_f32 v[182:183], v[132:133], v[116:117], v[182:183]
	v_pk_fma_f32 v[194:195], v[134:135], v[6:7], v[194:195]
	v_pk_fma_f32 v[196:197], v[134:135], v[22:23], v[196:197]
	v_pk_fma_f32 v[198:199], v[134:135], v[38:39], v[198:199]
	v_pk_fma_f32 v[200:201], v[134:135], v[54:55], v[200:201]
	v_pk_fma_f32 v[202:203], v[134:135], v[70:71], v[202:203]
	v_pk_fma_f32 v[204:205], v[134:135], v[86:87], v[204:205]
	v_pk_fma_f32 v[206:207], v[134:135], v[102:103], v[206:207]
	v_pk_fma_f32 v[182:183], v[134:135], v[118:119], v[182:183]
	v_pk_fma_f32 v[194:195], v[136:137], v[8:9], v[194:195]
	v_pk_fma_f32 v[196:197], v[136:137], v[24:25], v[196:197]
	v_pk_fma_f32 v[198:199], v[136:137], v[40:41], v[198:199]
	v_pk_fma_f32 v[200:201], v[136:137], v[56:57], v[200:201]
	v_pk_fma_f32 v[202:203], v[136:137], v[72:73], v[202:203]
	v_pk_fma_f32 v[204:205], v[136:137], v[88:89], v[204:205]
	v_pk_fma_f32 v[206:207], v[136:137], v[104:105], v[206:207]
	v_pk_fma_f32 v[182:183], v[136:137], v[120:121], v[182:183]
	v_pk_fma_f32 v[194:195], v[138:139], v[10:11], v[194:195]
	v_pk_fma_f32 v[196:197], v[138:139], v[26:27], v[196:197]
	v_pk_fma_f32 v[198:199], v[138:139], v[42:43], v[198:199]
	v_pk_fma_f32 v[200:201], v[138:139], v[58:59], v[200:201]
	v_pk_fma_f32 v[202:203], v[138:139], v[74:75], v[202:203]
	v_pk_fma_f32 v[204:205], v[138:139], v[90:91], v[204:205]
	v_pk_fma_f32 v[206:207], v[138:139], v[106:107], v[206:207]
	v_pk_fma_f32 v[182:183], v[138:139], v[122:123], v[182:183]
	v_pk_fma_f32 v[194:195], v[140:141], v[12:13], v[194:195]
	v_pk_fma_f32 v[196:197], v[140:141], v[28:29], v[196:197]
	v_pk_fma_f32 v[198:199], v[140:141], v[44:45], v[198:199]
	v_pk_fma_f32 v[200:201], v[140:141], v[60:61], v[200:201]
	v_pk_fma_f32 v[202:203], v[140:141], v[76:77], v[202:203]
	v_pk_fma_f32 v[204:205], v[140:141], v[92:93], v[204:205]
	v_pk_fma_f32 v[206:207], v[140:141], v[108:109], v[206:207]
	v_pk_fma_f32 v[182:183], v[140:141], v[124:125], v[182:183]
	v_pk_fma_f32 v[194:195], v[142:143], v[14:15], v[194:195]
	v_pk_fma_f32 v[196:197], v[142:143], v[30:31], v[196:197]
	v_pk_fma_f32 v[198:199], v[142:143], v[46:47], v[198:199]
	v_pk_fma_f32 v[200:201], v[142:143], v[62:63], v[200:201]
	v_pk_fma_f32 v[202:203], v[142:143], v[78:79], v[202:203]
	v_pk_fma_f32 v[204:205], v[142:143], v[94:95], v[204:205]
	v_pk_fma_f32 v[206:207], v[142:143], v[110:111], v[206:207]
	v_pk_fma_f32 v[182:183], v[142:143], v[126:127], v[182:183]
	v_pk_fma_f32 v[194:195], v[144:145], v[16:17], v[194:195]
	v_pk_fma_f32 v[196:197], v[144:145], v[32:33], v[196:197]
	v_pk_fma_f32 v[198:199], v[144:145], v[48:49], v[198:199]
	v_pk_fma_f32 v[200:201], v[144:145], v[64:65], v[200:201]
	v_pk_fma_f32 v[202:203], v[144:145], v[80:81], v[202:203]
	v_pk_fma_f32 v[204:205], v[144:145], v[96:97], v[204:205]
	v_pk_fma_f32 v[206:207], v[144:145], v[112:113], v[206:207]
	v_pk_fma_f32 v[182:183], v[144:145], v[128:129], v[182:183]
	v_add_f32_e32 v194, v194, v195
	v_add_f32_e32 v196, v196, v197
	v_add_f32_e32 v198, v198, v199
	v_add_f32_e32 v200, v200, v201
	v_add_f32_e32 v202, v202, v203
	v_add_f32_e32 v204, v204, v205
	v_add_f32_e32 v206, v206, v207
	v_add_f32_e32 v182, v182, v183
	s_nop 1
	v_permlane32_swap_b32_e32 v194, v202
	v_permlane32_swap_b32_e32 v196, v204
	v_permlane32_swap_b32_e32 v198, v206
	v_permlane32_swap_b32_e32 v200, v182
	v_add_f32_e32 v194, v194, v202
	v_add_f32_e32 v196, v196, v204
	v_add_f32_e32 v198, v198, v206
	v_add_f32_e32 v200, v200, v182
	s_nop 1
	v_permlane16_swap_b32_e32 v194, v198
	v_permlane16_swap_b32_e32 v196, v200
	v_add_f32_e32 v194, v194, v198
	v_add_f32_e32 v196, v196, v200
	s_nop 1
	v_add_f32_dpp v233, v194, v194 row_ror:8 row_mask:0xf bank_mask:0x3
	v_add_f32_dpp v233, v196, v196 row_ror:8 row_mask:0xf bank_mask:0xc
; __device__ __forceinline__ void fg_tail(const Args& a, int l, LAS unsigned char* lds, const int tid) {
;     ...
;             for (int j = 0; j < 4; ++j) { const int row = rowc + jb + j; rs4v[j] = *(const f32x4*)(rowss + (size_t)row * 4); w0v[j] = *(const u32x4*)(H + (size_t)row * DM + 16 * lane); w1v[j] = *(const u32x4*)(H + (size_t)row * DM + 16 * lane + 8); }
; #pragma unroll
;             for (int j = 0; j < 4; ++j) {
;                 const int row = rowc + jb + j;
;                 const f32x4 rs4 = rs4v[j]; const u32x4 w0 = w0v[j], w1 = w1v[j];
;                 const float r = 1.0f / sqrtf(((rs4[0] + rs4[1]) + (rs4[2] + rs4[3])) * (1.0f / 1024.0f) + EPS);
;                 float h[16];
; #pragma unroll
;                 for (int i = 0; i < 4; ++i) { h[2 * i] = __uint_as_float(w0[i] << 16); h[2 * i + 1] = __uint_as_float(w0[i] & 0xffff0000u); h[8 + 2 * i] = __uint_as_float(w1[i] << 16); h[8 + 2 * i + 1] = __uint_as_float(w1[i] & 0xffff0000u); }
; #pragma unroll
;                 for (int q = 0; q < 4; ++q) { h[4 * q] = h[4 * q] * r + sh[q][0]; h[4 * q + 1] = h[4 * q + 1] * r + sh[q][1]; h[4 * q + 2] = h[4 * q + 2] * r + sh[q][2]; h[4 * q + 3] = h[4 * q + 3] * r + sh[q][3]; }
;                 float d8[8];
; #pragma unroll
;                 for (int j8 = 0; j8 < 8; ++j8) { float acc = 0.f;
; #pragma unroll
;                     for (int q = 0; q < 4; ++q) { const f32x4 w = wl[(j8 * 4 + q) * 64 + lane]; acc += (h[4 * q] * w[0] + h[4 * q + 1] * w[1]) + (h[4 * q + 2] * w[2] + h[4 * q + 3] * w[3]); }
;                     d8[j8] = acc; }
;                 const float tot = reduce8(d8, lane);
	v_lshlrev_b32_e32 v130, 16, v154
	v_and_b32_e32 v131, 0xffff0000, v154
	v_lshlrev_b32_e32 v132, 16, v155
	v_and_b32_e32 v133, 0xffff0000, v155
	v_lshlrev_b32_e32 v134, 16, v156
	v_and_b32_e32 v135, 0xffff0000, v156
	v_lshlrev_b32_e32 v136, 16, v157
	v_and_b32_e32 v137, 0xffff0000, v157
	v_lshlrev_b32_e32 v138, 16, v158
	v_and_b32_e32 v139, 0xffff0000, v158
	v_lshlrev_b32_e32 v140, 16, v159
	v_and_b32_e32 v141, 0xffff0000, v159
	v_lshlrev_b32_e32 v142, 16, v160
	v_and_b32_e32 v143, 0xffff0000, v160
	v_lshlrev_b32_e32 v144, 16, v161
	v_and_b32_e32 v145, 0xffff0000, v161
	global_load_dwordx4 v[154:157], v184, s[94:95] offset:2048
	global_load_dwordx4 v[158:161], v184, s[94:95] offset:2064
	v_add_u32_e32 v184, 0x1000, v184
	v_pk_mul_f32 v[194:195], v[130:131], v[2:3]
	v_pk_mul_f32 v[196:197], v[130:131], v[18:19]
	v_pk_mul_f32 v[198:199], v[130:131], v[34:35]
	v_pk_mul_f32 v[200:201], v[130:131], v[50:51]
	v_pk_mul_f32 v[202:203], v[130:131], v[66:67]
	v_pk_mul_f32 v[204:205], v[130:131], v[82:83]
	v_pk_mul_f32 v[206:207], v[130:131], v[98:99]
	v_pk_mul_f32 v[182:183], v[130:131], v[114:115]
	v_pk_fma_f32 v[194:195], v[132:133], v[4:5], v[194:195]
	v_pk_fma_f32 v[196:197], v[132:133], v[20:21], v[196:197]
	v_pk_fma_f32 v[198:199], v[132:133], v[36:37], v[198:199]
	v_pk_fma_f32 v[200:201], v[132:133], v[52:53], v[200:201]
	v_pk_fma_f32 v[202:203], v[132:133], v[68:69], v[202:203]
	v_pk_fma_f32 v[204:205], v[132:133], v[84:85], v[204:205]
	v_pk_fma_f32 v[206:207], v[132:133], v[100:101], v[206:207]
	v_pk_fma_f32 v[182:183], v[132:133], v[116:117], v[182:183]
	v_pk_fma_f32 v[194:195], v[134:135], v[6:7], v[194:195]
	v_pk_fma_f32 v[196:197], v[134:135], v[22:23], v[196:197]
	v_pk_fma_f32 v[198:199], v[134:135], v[38:39], v[198:199]
	v_pk_fma_f32 v[200:201], v[134:135], v[54:55], v[200:201]
	v_pk_fma_f32 v[202:203], v[134:135], v[70:71], v[202:203]
	v_pk_fma_f32 v[204:205], v[134:135], v[86:87], v[204:205]
	v_pk_fma_f32 v[206:207], v[134:135], v[102:103], v[206:207]
	v_pk_fma_f32 v[182:183], v[134:135], v[118:119], v[182:183]
	v_pk_fma_f32 v[194:195], v[136:137], v[8:9], v[194:195]
	v_pk_fma_f32 v[196:197], v[136:137], v[24:25], v[196:197]
	v_pk_fma_f32 v[198:199], v[136:137], v[40:41], v[198:199]
	v_pk_fma_f32 v[200:201], v[136:137], v[56:57], v[200:201]
	v_pk_fma_f32 v[202:203], v[136:137], v[72:73], v[202:203]
	v_pk_fma_f32 v[204:205], v[136:137], v[88:89], v[204:205]
	v_pk_fma_f32 v[206:207], v[136:137], v[104:105], v[206:207]
	v_pk_fma_f32 v[182:183], v[136:137], v[120:121], v[182:183]
	v_pk_fma_f32 v[194:195], v[138:139], v[10:11], v[194:195]
	v_pk_fma_f32 v[196:197], v[138:139], v[26:27], v[196:197]
	v_pk_fma_f32 v[198:199], v[138:139], v[42:43], v[198:199]
	v_pk_fma_f32 v[200:201], v[138:139], v[58:59], v[200:201]
	v_pk_fma_f32 v[202:203], v[138:139], v[74:75], v[202:203]
	v_pk_fma_f32 v[204:205], v[138:139], v[90:91], v[204:205]
	v_pk_fma_f32 v[206:207], v[138:139], v[106:107], v[206:207]
	v_pk_fma_f32 v[182:183], v[138:139], v[122:123], v[182:183]
	v_pk_fma_f32 v[194:195], v[140:141], v[12:13], v[194:195]
	v_pk_fma_f32 v[196:197], v[140:141], v[28:29], v[196:197]
	v_pk_fma_f32 v[198:199], v[140:141], v[44:45], v[198:199]
	v_pk_fma_f32 v[200:201], v[140:141], v[60:61], v[200:201]
	v_pk_fma_f32 v[202:203], v[140:141], v[76:77], v[202:203]
	v_pk_fma_f32 v[204:205], v[140:141], v[92:93], v[204:205]
	v_pk_fma_f32 v[206:207], v[140:141], v[108:109], v[206:207]
	v_pk_fma_f32 v[182:183], v[140:141], v[124:125], v[182:183]
	v_pk_fma_f32 v[194:195], v[142:143], v[14:15], v[194:195]
	v_pk_fma_f32 v[196:197], v[142:143], v[30:31], v[196:197]
	v_pk_fma_f32 v[198:199], v[142:143], v[46:47], v[198:199]
	v_pk_fma_f32 v[200:201], v[142:143], v[62:63], v[200:201]
	v_pk_fma_f32 v[202:203], v[142:143], v[78:79], v[202:203]
	v_pk_fma_f32 v[204:205], v[142:143], v[94:95], v[204:205]
	v_pk_fma_f32 v[206:207], v[142:143], v[110:111], v[206:207]
	v_pk_fma_f32 v[182:183], v[142:143], v[126:127], v[182:183]
	v_pk_fma_f32 v[194:195], v[144:145], v[16:17], v[194:195]
	v_pk_fma_f32 v[196:197], v[144:145], v[32:33], v[196:197]
	v_pk_fma_f32 v[198:199], v[144:145], v[48:49], v[198:199]
	v_pk_fma_f32 v[200:201], v[144:145], v[64:65], v[200:201]
	v_pk_fma_f32 v[202:203], v[144:145], v[80:81], v[202:203]
	v_pk_fma_f32 v[204:205], v[144:145], v[96:97], v[204:205]
	v_pk_fma_f32 v[206:207], v[144:145], v[112:113], v[206:207]
	v_pk_fma_f32 v[182:183], v[144:145], v[128:129], v[182:183]
	v_add_f32_e32 v194, v194, v195
	v_add_f32_e32 v196, v196, v197
	v_add_f32_e32 v198, v198, v199
	v_add_f32_e32 v200, v200, v201
	v_add_f32_e32 v202, v202, v203
	v_add_f32_e32 v204, v204, v205
	v_add_f32_e32 v206, v206, v207
	v_add_f32_e32 v182, v182, v183
	s_nop 1
	v_permlane32_swap_b32_e32 v194, v202
	v_permlane32_swap_b32_e32 v196, v204
	v_permlane32_swap_b32_e32 v198, v206
	v_permlane32_swap_b32_e32 v200, v182
	v_add_f32_e32 v194, v194, v202
	v_add_f32_e32 v196, v196, v204
	v_add_f32_e32 v198, v198, v206
	v_add_f32_e32 v200, v200, v182
	s_nop 1
	v_permlane16_swap_b32_e32 v194, v198
	v_permlane16_swap_b32_e32 v196, v200
	v_add_f32_e32 v194, v194, v198
	v_add_f32_e32 v196, v196, v200
	s_nop 1
	v_add_f32_dpp v234, v194, v194 row_ror:8 row_mask:0xf bank_mask:0x3
	v_add_f32_dpp v234, v196, v196 row_ror:8 row_mask:0xf bank_mask:0xc
	v_lshlrev_b32_e32 v130, 16, v162
	v_and_b32_e32 v131, 0xffff0000, v162
	v_lshlrev_b32_e32 v132, 16, v163
	v_and_b32_e32 v133, 0xffff0000, v163
	v_lshlrev_b32_e32 v134, 16, v164
	v_and_b32_e32 v135, 0xffff0000, v164
	v_lshlrev_b32_e32 v136, 16, v165
	v_and_b32_e32 v137, 0xffff0000, v165
	v_lshlrev_b32_e32 v138, 16, v166
	v_and_b32_e32 v139, 0xffff0000, v166
; __device__ __forceinline__ void fg_tail(const Args& a, int l, LAS unsigned char* lds, const int tid) {
;     ...
;             for (int j = 0; j < 4; ++j) { const int row = rowc + jb + j; rs4v[j] = *(const f32x4*)(rowss + (size_t)row * 4); w0v[j] = *(const u32x4*)(H + (size_t)row * DM + 16 * lane); w1v[j] = *(const u32x4*)(H + (size_t)row * DM + 16 * lane + 8); }
; #pragma unroll
;             for (int j = 0; j < 4; ++j) {
;                 const int row = rowc + jb + j;
;                 const f32x4 rs4 = rs4v[j]; const u32x4 w0 = w0v[j], w1 = w1v[j];
;                 const float r = 1.0f / sqrtf(((rs4[0] + rs4[1]) + (rs4[2] + rs4[3])) * (1.0f / 1024.0f) + EPS);
;                 float h[16];
; #pragma unroll
;                 for (int i = 0; i < 4; ++i) { h[2 * i] = __uint_as_float(w0[i] << 16); h[2 * i + 1] = __uint_as_float(w0[i] & 0xffff0000u); h[8 + 2 * i] = __uint_as_float(w1[i] << 16); h[8 + 2 * i + 1] = __uint_as_float(w1[i] & 0xffff0000u); }
; #pragma unroll
;                 for (int q = 0; q < 4; ++q) { h[4 * q] = h[4 * q] * r + sh[q][0]; h[4 * q + 1] = h[4 * q + 1] * r + sh[q][1]; h[4 * q + 2] = h[4 * q + 2] * r + sh[q][2]; h[4 * q + 3] = h[4 * q + 3] * r + sh[q][3]; }
;                 float d8[8];
; #pragma unroll
;                 for (int j8 = 0; j8 < 8; ++j8) { float acc = 0.f;
; #pragma unroll
;                     for (int q = 0; q < 4; ++q) { const f32x4 w = wl[(j8 * 4 + q) * 64 + lane]; acc += (h[4 * q] * w[0] + h[4 * q + 1] * w[1]) + (h[4 * q + 2] * w[2] + h[4 * q + 3] * w[3]); }
;                     d8[j8] = acc; }
;                 const float tot = reduce8(d8, lane);
	v_lshlrev_b32_e32 v140, 16, v167
	v_and_b32_e32 v141, 0xffff0000, v167
	v_lshlrev_b32_e32 v142, 16, v168
	v_and_b32_e32 v143, 0xffff0000, v168
	v_lshlrev_b32_e32 v144, 16, v169
	v_and_b32_e32 v145, 0xffff0000, v169
	global_load_dwordx4 v[162:165], v184, s[94:95]
	global_load_dwordx4 v[166:169], v184, s[94:95] offset:16
	v_pk_mul_f32 v[194:195], v[130:131], v[2:3]
	v_pk_mul_f32 v[196:197], v[130:131], v[18:19]
	v_pk_mul_f32 v[198:199], v[130:131], v[34:35]
	v_pk_mul_f32 v[200:201], v[130:131], v[50:51]
	v_pk_mul_f32 v[202:203], v[130:131], v[66:67]
	v_pk_mul_f32 v[204:205], v[130:131], v[82:83]
	v_pk_mul_f32 v[206:207], v[130:131], v[98:99]
	v_pk_mul_f32 v[182:183], v[130:131], v[114:115]
	v_pk_fma_f32 v[194:195], v[132:133], v[4:5], v[194:195]
	v_pk_fma_f32 v[196:197], v[132:133], v[20:21], v[196:197]
	v_pk_fma_f32 v[198:199], v[132:133], v[36:37], v[198:199]
	v_pk_fma_f32 v[200:201], v[132:133], v[52:53], v[200:201]
	v_pk_fma_f32 v[202:203], v[132:133], v[68:69], v[202:203]
	v_pk_fma_f32 v[204:205], v[132:133], v[84:85], v[204:205]
	v_pk_fma_f32 v[206:207], v[132:133], v[100:101], v[206:207]
	v_pk_fma_f32 v[182:183], v[132:133], v[116:117], v[182:183]
	v_pk_fma_f32 v[194:195], v[134:135], v[6:7], v[194:195]
	v_pk_fma_f32 v[196:197], v[134:135], v[22:23], v[196:197]
	v_pk_fma_f32 v[198:199], v[134:135], v[38:39], v[198:199]
	v_pk_fma_f32 v[200:201], v[134:135], v[54:55], v[200:201]
	v_pk_fma_f32 v[202:203], v[134:135], v[70:71], v[202:203]
	v_pk_fma_f32 v[204:205], v[134:135], v[86:87], v[204:205]
	v_pk_fma_f32 v[206:207], v[134:135], v[102:103], v[206:207]
	v_pk_fma_f32 v[182:183], v[134:135], v[118:119], v[182:183]
	v_pk_fma_f32 v[194:195], v[136:137], v[8:9], v[194:195]
	v_pk_fma_f32 v[196:197], v[136:137], v[24:25], v[196:197]
	v_pk_fma_f32 v[198:199], v[136:137], v[40:41], v[198:199]
	v_pk_fma_f32 v[200:201], v[136:137], v[56:57], v[200:201]
	v_pk_fma_f32 v[202:203], v[136:137], v[72:73], v[202:203]
	v_pk_fma_f32 v[204:205], v[136:137], v[88:89], v[204:205]
	v_pk_fma_f32 v[206:207], v[136:137], v[104:105], v[206:207]
	v_pk_fma_f32 v[182:183], v[136:137], v[120:121], v[182:183]
	v_pk_fma_f32 v[194:195], v[138:139], v[10:11], v[194:195]
	v_pk_fma_f32 v[196:197], v[138:139], v[26:27], v[196:197]
	v_pk_fma_f32 v[198:199], v[138:139], v[42:43], v[198:199]
	v_pk_fma_f32 v[200:201], v[138:139], v[58:59], v[200:201]
	v_pk_fma_f32 v[202:203], v[138:139], v[74:75], v[202:203]
	v_pk_fma_f32 v[204:205], v[138:139], v[90:91], v[204:205]
	v_pk_fma_f32 v[206:207], v[138:139], v[106:107], v[206:207]
	v_pk_fma_f32 v[182:183], v[138:139], v[122:123], v[182:183]
	v_pk_fma_f32 v[194:195], v[140:141], v[12:13], v[194:195]
	v_pk_fma_f32 v[196:197], v[140:141], v[28:29], v[196:197]
	v_pk_fma_f32 v[198:199], v[140:141], v[44:45], v[198:199]
	v_pk_fma_f32 v[200:201], v[140:141], v[60:61], v[200:201]
	v_pk_fma_f32 v[202:203], v[140:141], v[76:77], v[202:203]
	v_pk_fma_f32 v[204:205], v[140:141], v[92:93], v[204:205]
	v_pk_fma_f32 v[206:207], v[140:141], v[108:109], v[206:207]
	v_pk_fma_f32 v[182:183], v[140:141], v[124:125], v[182:183]
	v_pk_fma_f32 v[194:195], v[142:143], v[14:15], v[194:195]
	v_pk_fma_f32 v[196:197], v[142:143], v[30:31], v[196:197]
	v_pk_fma_f32 v[198:199], v[142:143], v[46:47], v[198:199]
	v_pk_fma_f32 v[200:201], v[142:143], v[62:63], v[200:201]
	v_pk_fma_f32 v[202:203], v[142:143], v[78:79], v[202:203]
	v_pk_fma_f32 v[204:205], v[142:143], v[94:95], v[204:205]
	v_pk_fma_f32 v[206:207], v[142:143], v[110:111], v[206:207]
	v_pk_fma_f32 v[182:183], v[142:143], v[126:127], v[182:183]
	v_pk_fma_f32 v[194:195], v[144:145], v[16:17], v[194:195]
	v_pk_fma_f32 v[196:197], v[144:145], v[32:33], v[196:197]
	v_pk_fma_f32 v[198:199], v[144:145], v[48:49], v[198:199]
	v_pk_fma_f32 v[200:201], v[144:145], v[64:65], v[200:201]
	v_pk_fma_f32 v[202:203], v[144:145], v[80:81], v[202:203]
	v_pk_fma_f32 v[204:205], v[144:145], v[96:97], v[204:205]
	v_pk_fma_f32 v[206:207], v[144:145], v[112:113], v[206:207]
	v_pk_fma_f32 v[182:183], v[144:145], v[128:129], v[182:183]
	v_add_f32_e32 v194, v194, v195
	v_add_f32_e32 v196, v196, v197
	v_add_f32_e32 v198, v198, v199
	v_add_f32_e32 v200, v200, v201
	v_add_f32_e32 v202, v202, v203
	v_add_f32_e32 v204, v204, v205
	v_add_f32_e32 v206, v206, v207
	v_add_f32_e32 v182, v182, v183
	s_nop 1
	v_permlane32_swap_b32_e32 v194, v202
	v_permlane32_swap_b32_e32 v196, v204
	v_permlane32_swap_b32_e32 v198, v206
	v_permlane32_swap_b32_e32 v200, v182
	v_add_f32_e32 v194, v194, v202
	v_add_f32_e32 v196, v196, v204
	v_add_f32_e32 v198, v198, v206
	v_add_f32_e32 v200, v200, v182
	s_nop 1
	v_permlane16_swap_b32_e32 v194, v198
	v_permlane16_swap_b32_e32 v196, v200
	v_add_f32_e32 v194, v194, v198
	v_add_f32_e32 v196, v196, v200
	s_nop 1
	v_add_f32_dpp v235, v194, v194 row_ror:8 row_mask:0xf bank_mask:0x3
	v_add_f32_dpp v235, v196, v196 row_ror:8 row_mask:0xf bank_mask:0xc
	v_lshlrev_b32_e32 v130, 16, v170
	v_and_b32_e32 v131, 0xffff0000, v170
	v_lshlrev_b32_e32 v132, 16, v171
	v_and_b32_e32 v133, 0xffff0000, v171
	v_lshlrev_b32_e32 v134, 16, v172
	v_and_b32_e32 v135, 0xffff0000, v172
	v_lshlrev_b32_e32 v136, 16, v173
	v_and_b32_e32 v137, 0xffff0000, v173
	v_lshlrev_b32_e32 v138, 16, v174
	v_and_b32_e32 v139, 0xffff0000, v174
	v_lshlrev_b32_e32 v140, 16, v175
	v_and_b32_e32 v141, 0xffff0000, v175
	v_lshlrev_b32_e32 v142, 16, v176
	v_and_b32_e32 v143, 0xffff0000, v176
	v_lshlrev_b32_e32 v144, 16, v177
	v_and_b32_e32 v145, 0xffff0000, v177
	global_load_dwordx4 v[170:173], v184, s[94:95] offset:2048
	global_load_dwordx4 v[174:177], v184, s[94:95] offset:2064
	v_pk_mul_f32 v[194:195], v[130:131], v[2:3]
	v_pk_mul_f32 v[196:197], v[130:131], v[18:19]
; __device__ __forceinline__ void fg_tail(const Args& a, int l, LAS unsigned char* lds, const int tid) {
;     ...
;                 for (int i = 0; i < 4; ++i) { h[2 * i] = __uint_as_float(w0[i] << 16); h[2 * i + 1] = __uint_as_float(w0[i] & 0xffff0000u); h[8 + 2 * i] = __uint_as_float(w1[i] << 16); h[8 + 2 * i + 1] = __uint_as_float(w1[i] & 0xffff0000u); }
; #pragma unroll
;                 for (int q = 0; q < 4; ++q) { h[4 * q] = h[4 * q] * r + sh[q][0]; h[4 * q + 1] = h[4 * q + 1] * r + sh[q][1]; h[4 * q + 2] = h[4 * q + 2] * r + sh[q][2]; h[4 * q + 3] = h[4 * q + 3] * r + sh[q][3]; }
;                 float d8[8];
; #pragma unroll
;                 for (int j8 = 0; j8 < 8; ++j8) { float acc = 0.f;
; #pragma unroll
;                     for (int q = 0; q < 4; ++q) { const f32x4 w = wl[(j8 * 4 + q) * 64 + lane]; acc += (h[4 * q] * w[0] + h[4 * q + 1] * w[1]) + (h[4 * q + 2] * w[2] + h[4 * q + 3] * w[3]); }
;                     d8[j8] = acc; }
;                 const float tot = reduce8(d8, lane);
	v_pk_mul_f32 v[198:199], v[130:131], v[34:35]
	v_pk_mul_f32 v[200:201], v[130:131], v[50:51]
	v_pk_mul_f32 v[202:203], v[130:131], v[66:67]
	v_pk_mul_f32 v[204:205], v[130:131], v[82:83]
	v_pk_mul_f32 v[206:207], v[130:131], v[98:99]
	v_pk_mul_f32 v[182:183], v[130:131], v[114:115]
	v_pk_fma_f32 v[194:195], v[132:133], v[4:5], v[194:195]
	v_pk_fma_f32 v[196:197], v[132:133], v[20:21], v[196:197]
	v_pk_fma_f32 v[198:199], v[132:133], v[36:37], v[198:199]
	v_pk_fma_f32 v[200:201], v[132:133], v[52:53], v[200:201]
	v_pk_fma_f32 v[202:203], v[132:133], v[68:69], v[202:203]
	v_pk_fma_f32 v[204:205], v[132:133], v[84:85], v[204:205]
	v_pk_fma_f32 v[206:207], v[132:133], v[100:101], v[206:207]
	v_pk_fma_f32 v[182:183], v[132:133], v[116:117], v[182:183]
	v_pk_fma_f32 v[194:195], v[134:135], v[6:7], v[194:195]
	v_pk_fma_f32 v[196:197], v[134:135], v[22:23], v[196:197]
	v_pk_fma_f32 v[198:199], v[134:135], v[38:39], v[198:199]
	v_pk_fma_f32 v[200:201], v[134:135], v[54:55], v[200:201]
	v_pk_fma_f32 v[202:203], v[134:135], v[70:71], v[202:203]
	v_pk_fma_f32 v[204:205], v[134:135], v[86:87], v[204:205]
	v_pk_fma_f32 v[206:207], v[134:135], v[102:103], v[206:207]
	v_pk_fma_f32 v[182:183], v[134:135], v[118:119], v[182:183]
	v_pk_fma_f32 v[194:195], v[136:137], v[8:9], v[194:195]
	v_pk_fma_f32 v[196:197], v[136:137], v[24:25], v[196:197]
	v_pk_fma_f32 v[198:199], v[136:137], v[40:41], v[198:199]
	v_pk_fma_f32 v[200:201], v[136:137], v[56:57], v[200:201]
	v_pk_fma_f32 v[202:203], v[136:137], v[72:73], v[202:203]
	v_pk_fma_f32 v[204:205], v[136:137], v[88:89], v[204:205]
	v_pk_fma_f32 v[206:207], v[136:137], v[104:105], v[206:207]
	v_pk_fma_f32 v[182:183], v[136:137], v[120:121], v[182:183]
	v_pk_fma_f32 v[194:195], v[138:139], v[10:11], v[194:195]
	v_pk_fma_f32 v[196:197], v[138:139], v[26:27], v[196:197]
	v_pk_fma_f32 v[198:199], v[138:139], v[42:43], v[198:199]
	v_pk_fma_f32 v[200:201], v[138:139], v[58:59], v[200:201]
	v_pk_fma_f32 v[202:203], v[138:139], v[74:75], v[202:203]
	v_pk_fma_f32 v[204:205], v[138:139], v[90:91], v[204:205]
	v_pk_fma_f32 v[206:207], v[138:139], v[106:107], v[206:207]
	v_pk_fma_f32 v[182:183], v[138:139], v[122:123], v[182:183]
	v_pk_fma_f32 v[194:195], v[140:141], v[12:13], v[194:195]
	v_pk_fma_f32 v[196:197], v[140:141], v[28:29], v[196:197]
	v_pk_fma_f32 v[198:199], v[140:141], v[44:45], v[198:199]
	v_pk_fma_f32 v[200:201], v[140:141], v[60:61], v[200:201]
	v_pk_fma_f32 v[202:203], v[140:141], v[76:77], v[202:203]
	v_pk_fma_f32 v[204:205], v[140:141], v[92:93], v[204:205]
	v_pk_fma_f32 v[206:207], v[140:141], v[108:109], v[206:207]
	v_pk_fma_f32 v[182:183], v[140:141], v[124:125], v[182:183]
	v_pk_fma_f32 v[194:195], v[142:143], v[14:15], v[194:195]
	v_pk_fma_f32 v[196:197], v[142:143], v[30:31], v[196:197]
	v_pk_fma_f32 v[198:199], v[142:143], v[46:47], v[198:199]
	v_pk_fma_f32 v[200:201], v[142:143], v[62:63], v[200:201]
	v_pk_fma_f32 v[202:203], v[142:143], v[78:79], v[202:203]
	v_pk_fma_f32 v[204:205], v[142:143], v[94:95], v[204:205]
	v_pk_fma_f32 v[206:207], v[142:143], v[110:111], v[206:207]
	v_pk_fma_f32 v[182:183], v[142:143], v[126:127], v[182:183]
	v_pk_fma_f32 v[194:195], v[144:145], v[16:17], v[194:195]
	v_pk_fma_f32 v[196:197], v[144:145], v[32:33], v[196:197]
	v_pk_fma_f32 v[198:199], v[144:145], v[48:49], v[198:199]
	v_pk_fma_f32 v[200:201], v[144:145], v[64:65], v[200:201]
	v_pk_fma_f32 v[202:203], v[144:145], v[80:81], v[202:203]
	v_pk_fma_f32 v[204:205], v[144:145], v[96:97], v[204:205]
	v_pk_fma_f32 v[206:207], v[144:145], v[112:113], v[206:207]
	v_pk_fma_f32 v[182:183], v[144:145], v[128:129], v[182:183]
	v_add_f32_e32 v194, v194, v195
	v_add_f32_e32 v196, v196, v197
	v_add_f32_e32 v198, v198, v199
	v_add_f32_e32 v200, v200, v201
	v_add_f32_e32 v202, v202, v203
	v_add_f32_e32 v204, v204, v205
	v_add_f32_e32 v206, v206, v207
	v_add_f32_e32 v182, v182, v183
	s_nop 1
	v_permlane32_swap_b32_e32 v194, v202
	v_permlane32_swap_b32_e32 v196, v204
	v_permlane32_swap_b32_e32 v198, v206
	v_permlane32_swap_b32_e32 v200, v182
	v_add_f32_e32 v194, v194, v202
	v_add_f32_e32 v196, v196, v204
	v_add_f32_e32 v198, v198, v206
	v_add_f32_e32 v200, v200, v182
	s_nop 1
	v_permlane16_swap_b32_e32 v194, v198
	v_permlane16_swap_b32_e32 v196, v200
	v_add_f32_e32 v194, v194, v198
	v_add_f32_e32 v196, v196, v200
	s_nop 1
	v_add_f32_dpp v236, v194, v194 row_ror:8 row_mask:0xf bank_mask:0x3
	v_add_f32_dpp v236, v196, v196 row_ror:8 row_mask:0xf bank_mask:0xc
	s_waitcnt vmcnt(6)
; __device__ __forceinline__ void fg_tail(const Args& a, int l, LAS unsigned char* lds, const int tid) {
;     ...
;                 for (int i = 0; i < 4; ++i) { h[2 * i] = __uint_as_float(w0[i] << 16); h[2 * i + 1] = __uint_as_float(w0[i] & 0xffff0000u); h[8 + 2 * i] = __uint_as_float(w1[i] << 16); h[8 + 2 * i + 1] = __uint_as_float(w1[i] & 0xffff0000u); }
; #pragma unroll
;                 for (int q = 0; q < 4; ++q) { h[4 * q] = h[4 * q] * r + sh[q][0]; h[4 * q + 1] = h[4 * q + 1] * r + sh[q][1]; h[4 * q + 2] = h[4 * q + 2] * r + sh[q][2]; h[4 * q + 3] = h[4 * q + 3] * r + sh[q][3]; }
;                 float d8[8];
; #pragma unroll
;                 for (int j8 = 0; j8 < 8; ++j8) { float acc = 0.f;
; #pragma unroll
;                     for (int q = 0; q < 4; ++q) { const f32x4 w = wl[(j8 * 4 + q) * 64 + lane]; acc += (h[4 * q] * w[0] + h[4 * q + 1] * w[1]) + (h[4 * q + 2] * w[2] + h[4 * q + 3] * w[3]); }
;                     d8[j8] = acc; }
;                 const float tot = reduce8(d8, lane);
	v_lshlrev_b32_e32 v130, 16, v146
	v_and_b32_e32 v131, 0xffff0000, v146
	v_lshlrev_b32_e32 v132, 16, v147
	v_and_b32_e32 v133, 0xffff0000, v147
	v_lshlrev_b32_e32 v134, 16, v148
	v_and_b32_e32 v135, 0xffff0000, v148
	v_lshlrev_b32_e32 v136, 16, v149
	v_and_b32_e32 v137, 0xffff0000, v149
	v_lshlrev_b32_e32 v138, 16, v150
	v_and_b32_e32 v139, 0xffff0000, v150
	v_lshlrev_b32_e32 v140, 16, v151
	v_and_b32_e32 v141, 0xffff0000, v151
	v_lshlrev_b32_e32 v142, 16, v152
	v_and_b32_e32 v143, 0xffff0000, v152
	v_lshlrev_b32_e32 v144, 16, v153
	v_and_b32_e32 v145, 0xffff0000, v153
	v_pk_mul_f32 v[194:195], v[130:131], v[2:3]
	v_pk_mul_f32 v[196:197], v[130:131], v[18:19]
	v_pk_mul_f32 v[198:199], v[130:131], v[34:35]
	v_pk_mul_f32 v[200:201], v[130:131], v[50:51]
	v_pk_mul_f32 v[202:203], v[130:131], v[66:67]
	v_pk_mul_f32 v[204:205], v[130:131], v[82:83]
	v_pk_mul_f32 v[206:207], v[130:131], v[98:99]
	v_pk_mul_f32 v[182:183], v[130:131], v[114:115]
	v_pk_fma_f32 v[194:195], v[132:133], v[4:5], v[194:195]
	v_pk_fma_f32 v[196:197], v[132:133], v[20:21], v[196:197]
	v_pk_fma_f32 v[198:199], v[132:133], v[36:37], v[198:199]
	v_pk_fma_f32 v[200:201], v[132:133], v[52:53], v[200:201]
	v_pk_fma_f32 v[202:203], v[132:133], v[68:69], v[202:203]
	v_pk_fma_f32 v[204:205], v[132:133], v[84:85], v[204:205]
	v_pk_fma_f32 v[206:207], v[132:133], v[100:101], v[206:207]
	v_pk_fma_f32 v[182:183], v[132:133], v[116:117], v[182:183]
	v_pk_fma_f32 v[194:195], v[134:135], v[6:7], v[194:195]
	v_pk_fma_f32 v[196:197], v[134:135], v[22:23], v[196:197]
	v_pk_fma_f32 v[198:199], v[134:135], v[38:39], v[198:199]
	v_pk_fma_f32 v[200:201], v[134:135], v[54:55], v[200:201]
	v_pk_fma_f32 v[202:203], v[134:135], v[70:71], v[202:203]
	v_pk_fma_f32 v[204:205], v[134:135], v[86:87], v[204:205]
	v_pk_fma_f32 v[206:207], v[134:135], v[102:103], v[206:207]
	v_pk_fma_f32 v[182:183], v[134:135], v[118:119], v[182:183]
	v_pk_fma_f32 v[194:195], v[136:137], v[8:9], v[194:195]
	v_pk_fma_f32 v[196:197], v[136:137], v[24:25], v[196:197]
	v_pk_fma_f32 v[198:199], v[136:137], v[40:41], v[198:199]
	v_pk_fma_f32 v[200:201], v[136:137], v[56:57], v[200:201]
	v_pk_fma_f32 v[202:203], v[136:137], v[72:73], v[202:203]
	v_pk_fma_f32 v[204:205], v[136:137], v[88:89], v[204:205]
	v_pk_fma_f32 v[206:207], v[136:137], v[104:105], v[206:207]
	v_pk_fma_f32 v[182:183], v[136:137], v[120:121], v[182:183]
	v_pk_fma_f32 v[194:195], v[138:139], v[10:11], v[194:195]
	v_pk_fma_f32 v[196:197], v[138:139], v[26:27], v[196:197]
	v_pk_fma_f32 v[198:199], v[138:139], v[42:43], v[198:199]
	v_pk_fma_f32 v[200:201], v[138:139], v[58:59], v[200:201]
	v_pk_fma_f32 v[202:203], v[138:139], v[74:75], v[202:203]
	v_pk_fma_f32 v[204:205], v[138:139], v[90:91], v[204:205]
	v_pk_fma_f32 v[206:207], v[138:139], v[106:107], v[206:207]
	v_pk_fma_f32 v[182:183], v[138:139], v[122:123], v[182:183]
	v_pk_fma_f32 v[194:195], v[140:141], v[12:13], v[194:195]
	v_pk_fma_f32 v[196:197], v[140:141], v[28:29], v[196:197]
	v_pk_fma_f32 v[198:199], v[140:141], v[44:45], v[198:199]
	v_pk_fma_f32 v[200:201], v[140:141], v[60:61], v[200:201]
	v_pk_fma_f32 v[202:203], v[140:141], v[76:77], v[202:203]
	v_pk_fma_f32 v[204:205], v[140:141], v[92:93], v[204:205]
	v_pk_fma_f32 v[206:207], v[140:141], v[108:109], v[206:207]
	v_pk_fma_f32 v[182:183], v[140:141], v[124:125], v[182:183]
	v_pk_fma_f32 v[194:195], v[142:143], v[14:15], v[194:195]
	v_pk_fma_f32 v[196:197], v[142:143], v[30:31], v[196:197]
	v_pk_fma_f32 v[198:199], v[142:143], v[46:47], v[198:199]
	v_pk_fma_f32 v[200:201], v[142:143], v[62:63], v[200:201]
	v_pk_fma_f32 v[202:203], v[142:143], v[78:79], v[202:203]
	v_pk_fma_f32 v[204:205], v[142:143], v[94:95], v[204:205]
	v_pk_fma_f32 v[206:207], v[142:143], v[110:111], v[206:207]
	v_pk_fma_f32 v[182:183], v[142:143], v[126:127], v[182:183]
	v_pk_fma_f32 v[194:195], v[144:145], v[16:17], v[194:195]
	v_pk_fma_f32 v[196:197], v[144:145], v[32:33], v[196:197]
	v_pk_fma_f32 v[198:199], v[144:145], v[48:49], v[198:199]
	v_pk_fma_f32 v[200:201], v[144:145], v[64:65], v[200:201]
	v_pk_fma_f32 v[202:203], v[144:145], v[80:81], v[202:203]
	v_pk_fma_f32 v[204:205], v[144:145], v[96:97], v[204:205]
	v_pk_fma_f32 v[206:207], v[144:145], v[112:113], v[206:207]
	v_pk_fma_f32 v[182:183], v[144:145], v[128:129], v[182:183]
	v_add_f32_e32 v194, v194, v195
	v_add_f32_e32 v196, v196, v197
	v_add_f32_e32 v198, v198, v199
	v_add_f32_e32 v200, v200, v201
	v_add_f32_e32 v202, v202, v203
	v_add_f32_e32 v204, v204, v205
	v_add_f32_e32 v206, v206, v207
	v_add_f32_e32 v182, v182, v183
	s_nop 1
	v_permlane32_swap_b32_e32 v194, v202
	v_permlane32_swap_b32_e32 v196, v204
	v_permlane32_swap_b32_e32 v198, v206
	v_permlane32_swap_b32_e32 v200, v182
	v_add_f32_e32 v194, v194, v202
	v_add_f32_e32 v196, v196, v204
	v_add_f32_e32 v198, v198, v206
	v_add_f32_e32 v200, v200, v182
	s_nop 1
	v_permlane16_swap_b32_e32 v194, v198
	v_permlane16_swap_b32_e32 v196, v200
	v_add_f32_e32 v194, v194, v198
	v_add_f32_e32 v196, v196, v200
	s_nop 1
	v_add_f32_dpp v237, v194, v194 row_ror:8 row_mask:0xf bank_mask:0x3
	v_add_f32_dpp v237, v196, v196 row_ror:8 row_mask:0xf bank_mask:0xc
	s_waitcnt vmcnt(4)
; __device__ __forceinline__ void fg_tail(const Args& a, int l, LAS unsigned char* lds, const int tid) {
;     ...
;                 for (int i = 0; i < 4; ++i) { h[2 * i] = __uint_as_float(w0[i] << 16); h[2 * i + 1] = __uint_as_float(w0[i] & 0xffff0000u); h[8 + 2 * i] = __uint_as_float(w1[i] << 16); h[8 + 2 * i + 1] = __uint_as_float(w1[i] & 0xffff0000u); }
; #pragma unroll
;                 for (int q = 0; q < 4; ++q) { h[4 * q] = h[4 * q] * r + sh[q][0]; h[4 * q + 1] = h[4 * q + 1] * r + sh[q][1]; h[4 * q + 2] = h[4 * q + 2] * r + sh[q][2]; h[4 * q + 3] = h[4 * q + 3] * r + sh[q][3]; }
;                 float d8[8];
; #pragma unroll
;                 for (int j8 = 0; j8 < 8; ++j8) { float acc = 0.f;
; #pragma unroll
;                     for (int q = 0; q < 4; ++q) { const f32x4 w = wl[(j8 * 4 + q) * 64 + lane]; acc += (h[4 * q] * w[0] + h[4 * q + 1] * w[1]) + (h[4 * q + 2] * w[2] + h[4 * q + 3] * w[3]); }
;                     d8[j8] = acc; }
;                 const float tot = reduce8(d8, lane);
	v_lshlrev_b32_e32 v130, 16, v154
	v_and_b32_e32 v131, 0xffff0000, v154
	v_lshlrev_b32_e32 v132, 16, v155
	v_and_b32_e32 v133, 0xffff0000, v155
	v_lshlrev_b32_e32 v134, 16, v156
	v_and_b32_e32 v135, 0xffff0000, v156
	v_lshlrev_b32_e32 v136, 16, v157
	v_and_b32_e32 v137, 0xffff0000, v157
	v_lshlrev_b32_e32 v138, 16, v158
	v_and_b32_e32 v139, 0xffff0000, v158
	v_lshlrev_b32_e32 v140, 16, v159
	v_and_b32_e32 v141, 0xffff0000, v159
	v_lshlrev_b32_e32 v142, 16, v160
	v_and_b32_e32 v143, 0xffff0000, v160
	v_lshlrev_b32_e32 v144, 16, v161
	v_and_b32_e32 v145, 0xffff0000, v161
	v_pk_mul_f32 v[194:195], v[130:131], v[2:3]
	v_pk_mul_f32 v[196:197], v[130:131], v[18:19]
	v_pk_mul_f32 v[198:199], v[130:131], v[34:35]
	v_pk_mul_f32 v[200:201], v[130:131], v[50:51]
	v_pk_mul_f32 v[202:203], v[130:131], v[66:67]
	v_pk_mul_f32 v[204:205], v[130:131], v[82:83]
	v_pk_mul_f32 v[206:207], v[130:131], v[98:99]
	v_pk_mul_f32 v[182:183], v[130:131], v[114:115]
	v_pk_fma_f32 v[194:195], v[132:133], v[4:5], v[194:195]
	v_pk_fma_f32 v[196:197], v[132:133], v[20:21], v[196:197]
	v_pk_fma_f32 v[198:199], v[132:133], v[36:37], v[198:199]
	v_pk_fma_f32 v[200:201], v[132:133], v[52:53], v[200:201]
	v_pk_fma_f32 v[202:203], v[132:133], v[68:69], v[202:203]
	v_pk_fma_f32 v[204:205], v[132:133], v[84:85], v[204:205]
	v_pk_fma_f32 v[206:207], v[132:133], v[100:101], v[206:207]
	v_pk_fma_f32 v[182:183], v[132:133], v[116:117], v[182:183]
	v_pk_fma_f32 v[194:195], v[134:135], v[6:7], v[194:195]
	v_pk_fma_f32 v[196:197], v[134:135], v[22:23], v[196:197]
	v_pk_fma_f32 v[198:199], v[134:135], v[38:39], v[198:199]
	v_pk_fma_f32 v[200:201], v[134:135], v[54:55], v[200:201]
	v_pk_fma_f32 v[202:203], v[134:135], v[70:71], v[202:203]
	v_pk_fma_f32 v[204:205], v[134:135], v[86:87], v[204:205]
	v_pk_fma_f32 v[206:207], v[134:135], v[102:103], v[206:207]
	v_pk_fma_f32 v[182:183], v[134:135], v[118:119], v[182:183]
	v_pk_fma_f32 v[194:195], v[136:137], v[8:9], v[194:195]
	v_pk_fma_f32 v[196:197], v[136:137], v[24:25], v[196:197]
	v_pk_fma_f32 v[198:199], v[136:137], v[40:41], v[198:199]
	v_pk_fma_f32 v[200:201], v[136:137], v[56:57], v[200:201]
	v_pk_fma_f32 v[202:203], v[136:137], v[72:73], v[202:203]
	v_pk_fma_f32 v[204:205], v[136:137], v[88:89], v[204:205]
	v_pk_fma_f32 v[206:207], v[136:137], v[104:105], v[206:207]
	v_pk_fma_f32 v[182:183], v[136:137], v[120:121], v[182:183]
	v_pk_fma_f32 v[194:195], v[138:139], v[10:11], v[194:195]
	v_pk_fma_f32 v[196:197], v[138:139], v[26:27], v[196:197]
	v_pk_fma_f32 v[198:199], v[138:139], v[42:43], v[198:199]
	v_pk_fma_f32 v[200:201], v[138:139], v[58:59], v[200:201]
	v_pk_fma_f32 v[202:203], v[138:139], v[74:75], v[202:203]
	v_pk_fma_f32 v[204:205], v[138:139], v[90:91], v[204:205]
	v_pk_fma_f32 v[206:207], v[138:139], v[106:107], v[206:207]
	v_pk_fma_f32 v[182:183], v[138:139], v[122:123], v[182:183]
	v_pk_fma_f32 v[194:195], v[140:141], v[12:13], v[194:195]
	v_pk_fma_f32 v[196:197], v[140:141], v[28:29], v[196:197]
	v_pk_fma_f32 v[198:199], v[140:141], v[44:45], v[198:199]
	v_pk_fma_f32 v[200:201], v[140:141], v[60:61], v[200:201]
	v_pk_fma_f32 v[202:203], v[140:141], v[76:77], v[202:203]
	v_pk_fma_f32 v[204:205], v[140:141], v[92:93], v[204:205]
	v_pk_fma_f32 v[206:207], v[140:141], v[108:109], v[206:207]
	v_pk_fma_f32 v[182:183], v[140:141], v[124:125], v[182:183]
	v_pk_fma_f32 v[194:195], v[142:143], v[14:15], v[194:195]
	v_pk_fma_f32 v[196:197], v[142:143], v[30:31], v[196:197]
	v_pk_fma_f32 v[198:199], v[142:143], v[46:47], v[198:199]
	v_pk_fma_f32 v[200:201], v[142:143], v[62:63], v[200:201]
	v_pk_fma_f32 v[202:203], v[142:143], v[78:79], v[202:203]
	v_pk_fma_f32 v[204:205], v[142:143], v[94:95], v[204:205]
	v_pk_fma_f32 v[206:207], v[142:143], v[110:111], v[206:207]
	v_pk_fma_f32 v[182:183], v[142:143], v[126:127], v[182:183]
	v_pk_fma_f32 v[194:195], v[144:145], v[16:17], v[194:195]
	v_pk_fma_f32 v[196:197], v[144:145], v[32:33], v[196:197]
	v_pk_fma_f32 v[198:199], v[144:145], v[48:49], v[198:199]
	v_pk_fma_f32 v[200:201], v[144:145], v[64:65], v[200:201]
	v_pk_fma_f32 v[202:203], v[144:145], v[80:81], v[202:203]
	v_pk_fma_f32 v[204:205], v[144:145], v[96:97], v[204:205]
	v_pk_fma_f32 v[206:207], v[144:145], v[112:113], v[206:207]
	v_pk_fma_f32 v[182:183], v[144:145], v[128:129], v[182:183]
	v_add_f32_e32 v194, v194, v195
	v_add_f32_e32 v196, v196, v197
	v_add_f32_e32 v198, v198, v199
	v_add_f32_e32 v200, v200, v201
	v_add_f32_e32 v202, v202, v203
	v_add_f32_e32 v204, v204, v205
	v_add_f32_e32 v206, v206, v207
	v_add_f32_e32 v182, v182, v183
	s_nop 1
	v_permlane32_swap_b32_e32 v194, v202
	v_permlane32_swap_b32_e32 v196, v204
	v_permlane32_swap_b32_e32 v198, v206
	v_permlane32_swap_b32_e32 v200, v182
	v_add_f32_e32 v194, v194, v202
	v_add_f32_e32 v196, v196, v204
	v_add_f32_e32 v198, v198, v206
	v_add_f32_e32 v200, v200, v182
	s_nop 1
	v_permlane16_swap_b32_e32 v194, v198
	v_permlane16_swap_b32_e32 v196, v200
	v_add_f32_e32 v194, v194, v198
	v_add_f32_e32 v196, v196, v200
	s_nop 1
	v_add_f32_dpp v238, v194, v194 row_ror:8 row_mask:0xf bank_mask:0x3
	v_add_f32_dpp v238, v196, v196 row_ror:8 row_mask:0xf bank_mask:0xc
	s_waitcnt vmcnt(2)
; __device__ __forceinline__ void fg_tail(const Args& a, int l, LAS unsigned char* lds, const int tid) {
;     ...
;                 for (int i = 0; i < 4; ++i) { h[2 * i] = __uint_as_float(w0[i] << 16); h[2 * i + 1] = __uint_as_float(w0[i] & 0xffff0000u); h[8 + 2 * i] = __uint_as_float(w1[i] << 16); h[8 + 2 * i + 1] = __uint_as_float(w1[i] & 0xffff0000u); }
; #pragma unroll
;                 for (int q = 0; q < 4; ++q) { h[4 * q] = h[4 * q] * r + sh[q][0]; h[4 * q + 1] = h[4 * q + 1] * r + sh[q][1]; h[4 * q + 2] = h[4 * q + 2] * r + sh[q][2]; h[4 * q + 3] = h[4 * q + 3] * r + sh[q][3]; }
;                 float d8[8];
; #pragma unroll
;                 for (int j8 = 0; j8 < 8; ++j8) { float acc = 0.f;
; #pragma unroll
;                     for (int q = 0; q < 4; ++q) { const f32x4 w = wl[(j8 * 4 + q) * 64 + lane]; acc += (h[4 * q] * w[0] + h[4 * q + 1] * w[1]) + (h[4 * q + 2] * w[2] + h[4 * q + 3] * w[3]); }
;                     d8[j8] = acc; }
;                 const float tot = reduce8(d8, lane);
	v_lshlrev_b32_e32 v130, 16, v162
	v_and_b32_e32 v131, 0xffff0000, v162
	v_lshlrev_b32_e32 v132, 16, v163
	v_and_b32_e32 v133, 0xffff0000, v163
	v_lshlrev_b32_e32 v134, 16, v164
	v_and_b32_e32 v135, 0xffff0000, v164
	v_lshlrev_b32_e32 v136, 16, v165
	v_and_b32_e32 v137, 0xffff0000, v165
	v_lshlrev_b32_e32 v138, 16, v166
	v_and_b32_e32 v139, 0xffff0000, v166
	v_lshlrev_b32_e32 v140, 16, v167
	v_and_b32_e32 v141, 0xffff0000, v167
	v_lshlrev_b32_e32 v142, 16, v168
	v_and_b32_e32 v143, 0xffff0000, v168
	v_lshlrev_b32_e32 v144, 16, v169
	v_and_b32_e32 v145, 0xffff0000, v169
	v_pk_mul_f32 v[194:195], v[130:131], v[2:3]
	v_pk_mul_f32 v[196:197], v[130:131], v[18:19]
	v_pk_mul_f32 v[198:199], v[130:131], v[34:35]
	v_pk_mul_f32 v[200:201], v[130:131], v[50:51]
	v_pk_mul_f32 v[202:203], v[130:131], v[66:67]
	v_pk_mul_f32 v[204:205], v[130:131], v[82:83]
	v_pk_mul_f32 v[206:207], v[130:131], v[98:99]
	v_pk_mul_f32 v[182:183], v[130:131], v[114:115]
	v_pk_fma_f32 v[194:195], v[132:133], v[4:5], v[194:195]
	v_pk_fma_f32 v[196:197], v[132:133], v[20:21], v[196:197]
	v_pk_fma_f32 v[198:199], v[132:133], v[36:37], v[198:199]
	v_pk_fma_f32 v[200:201], v[132:133], v[52:53], v[200:201]
	v_pk_fma_f32 v[202:203], v[132:133], v[68:69], v[202:203]
	v_pk_fma_f32 v[204:205], v[132:133], v[84:85], v[204:205]
	v_pk_fma_f32 v[206:207], v[132:133], v[100:101], v[206:207]
	v_pk_fma_f32 v[182:183], v[132:133], v[116:117], v[182:183]
	v_pk_fma_f32 v[194:195], v[134:135], v[6:7], v[194:195]
	v_pk_fma_f32 v[196:197], v[134:135], v[22:23], v[196:197]
	v_pk_fma_f32 v[198:199], v[134:135], v[38:39], v[198:199]
	v_pk_fma_f32 v[200:201], v[134:135], v[54:55], v[200:201]
	v_pk_fma_f32 v[202:203], v[134:135], v[70:71], v[202:203]
	v_pk_fma_f32 v[204:205], v[134:135], v[86:87], v[204:205]
	v_pk_fma_f32 v[206:207], v[134:135], v[102:103], v[206:207]
	v_pk_fma_f32 v[182:183], v[134:135], v[118:119], v[182:183]
	v_pk_fma_f32 v[194:195], v[136:137], v[8:9], v[194:195]
	v_pk_fma_f32 v[196:197], v[136:137], v[24:25], v[196:197]
	v_pk_fma_f32 v[198:199], v[136:137], v[40:41], v[198:199]
	v_pk_fma_f32 v[200:201], v[136:137], v[56:57], v[200:201]
	v_pk_fma_f32 v[202:203], v[136:137], v[72:73], v[202:203]
	v_pk_fma_f32 v[204:205], v[136:137], v[88:89], v[204:205]
	v_pk_fma_f32 v[206:207], v[136:137], v[104:105], v[206:207]
	v_pk_fma_f32 v[182:183], v[136:137], v[120:121], v[182:183]
	v_pk_fma_f32 v[194:195], v[138:139], v[10:11], v[194:195]
	v_pk_fma_f32 v[196:197], v[138:139], v[26:27], v[196:197]
	v_pk_fma_f32 v[198:199], v[138:139], v[42:43], v[198:199]
	v_pk_fma_f32 v[200:201], v[138:139], v[58:59], v[200:201]
	v_pk_fma_f32 v[202:203], v[138:139], v[74:75], v[202:203]
	v_pk_fma_f32 v[204:205], v[138:139], v[90:91], v[204:205]
	v_pk_fma_f32 v[206:207], v[138:139], v[106:107], v[206:207]
	v_pk_fma_f32 v[182:183], v[138:139], v[122:123], v[182:183]
	v_pk_fma_f32 v[194:195], v[140:141], v[12:13], v[194:195]
	v_pk_fma_f32 v[196:197], v[140:141], v[28:29], v[196:197]
	v_pk_fma_f32 v[198:199], v[140:141], v[44:45], v[198:199]
	v_pk_fma_f32 v[200:201], v[140:141], v[60:61], v[200:201]
	v_pk_fma_f32 v[202:203], v[140:141], v[76:77], v[202:203]
	v_pk_fma_f32 v[204:205], v[140:141], v[92:93], v[204:205]
	v_pk_fma_f32 v[206:207], v[140:141], v[108:109], v[206:207]
	v_pk_fma_f32 v[182:183], v[140:141], v[124:125], v[182:183]
	v_pk_fma_f32 v[194:195], v[142:143], v[14:15], v[194:195]
	v_pk_fma_f32 v[196:197], v[142:143], v[30:31], v[196:197]
	v_pk_fma_f32 v[198:199], v[142:143], v[46:47], v[198:199]
	v_pk_fma_f32 v[200:201], v[142:143], v[62:63], v[200:201]
	v_pk_fma_f32 v[202:203], v[142:143], v[78:79], v[202:203]
	v_pk_fma_f32 v[204:205], v[142:143], v[94:95], v[204:205]
	v_pk_fma_f32 v[206:207], v[142:143], v[110:111], v[206:207]
	v_pk_fma_f32 v[182:183], v[142:143], v[126:127], v[182:183]
	v_pk_fma_f32 v[194:195], v[144:145], v[16:17], v[194:195]
	v_pk_fma_f32 v[196:197], v[144:145], v[32:33], v[196:197]
	v_pk_fma_f32 v[198:199], v[144:145], v[48:49], v[198:199]
	v_pk_fma_f32 v[200:201], v[144:145], v[64:65], v[200:201]
	v_pk_fma_f32 v[202:203], v[144:145], v[80:81], v[202:203]
	v_pk_fma_f32 v[204:205], v[144:145], v[96:97], v[204:205]
	v_pk_fma_f32 v[206:207], v[144:145], v[112:113], v[206:207]
	v_pk_fma_f32 v[182:183], v[144:145], v[128:129], v[182:183]
	v_add_f32_e32 v194, v194, v195
	v_add_f32_e32 v196, v196, v197
	v_add_f32_e32 v198, v198, v199
	v_add_f32_e32 v200, v200, v201
	v_add_f32_e32 v202, v202, v203
	v_add_f32_e32 v204, v204, v205
	v_add_f32_e32 v206, v206, v207
	v_add_f32_e32 v182, v182, v183
	s_nop 1
	v_permlane32_swap_b32_e32 v194, v202
	v_permlane32_swap_b32_e32 v196, v204
	v_permlane32_swap_b32_e32 v198, v206
	v_permlane32_swap_b32_e32 v200, v182
	v_add_f32_e32 v194, v194, v202
	v_add_f32_e32 v196, v196, v204
	v_add_f32_e32 v198, v198, v206
	v_add_f32_e32 v200, v200, v182
	s_nop 1
	v_permlane16_swap_b32_e32 v194, v198
	v_permlane16_swap_b32_e32 v196, v200
	v_add_f32_e32 v194, v194, v198
	v_add_f32_e32 v196, v196, v200
	s_nop 1
	v_add_f32_dpp v239, v194, v194 row_ror:8 row_mask:0xf bank_mask:0x3
	v_add_f32_dpp v239, v196, v196 row_ror:8 row_mask:0xf bank_mask:0xc
	s_waitcnt vmcnt(0)
; __device__ __forceinline__ void fg_tail(const Args& a, int l, LAS unsigned char* lds, const int tid) {
;     ...
;                 for (int i = 0; i < 4; ++i) { h[2 * i] = __uint_as_float(w0[i] << 16); h[2 * i + 1] = __uint_as_float(w0[i] & 0xffff0000u); h[8 + 2 * i] = __uint_as_float(w1[i] << 16); h[8 + 2 * i + 1] = __uint_as_float(w1[i] & 0xffff0000u); }
; #pragma unroll
;                 for (int q = 0; q < 4; ++q) { h[4 * q] = h[4 * q] * r + sh[q][0]; h[4 * q + 1] = h[4 * q + 1] * r + sh[q][1]; h[4 * q + 2] = h[4 * q + 2] * r + sh[q][2]; h[4 * q + 3] = h[4 * q + 3] * r + sh[q][3]; }
;                 float d8[8];
; #pragma unroll
;                 for (int j8 = 0; j8 < 8; ++j8) { float acc = 0.f;
; #pragma unroll
;                     for (int q = 0; q < 4; ++q) { const f32x4 w = wl[(j8 * 4 + q) * 64 + lane]; acc += (h[4 * q] * w[0] + h[4 * q + 1] * w[1]) + (h[4 * q + 2] * w[2] + h[4 * q + 3] * w[3]); }
;                     d8[j8] = acc; }
;                 const float tot = reduce8(d8, lane);
	v_lshlrev_b32_e32 v130, 16, v170
	v_and_b32_e32 v131, 0xffff0000, v170
	v_lshlrev_b32_e32 v132, 16, v171
	v_and_b32_e32 v133, 0xffff0000, v171
	v_lshlrev_b32_e32 v134, 16, v172
	v_and_b32_e32 v135, 0xffff0000, v172
	v_lshlrev_b32_e32 v136, 16, v173
	v_and_b32_e32 v137, 0xffff0000, v173
	v_lshlrev_b32_e32 v138, 16, v174
	v_and_b32_e32 v139, 0xffff0000, v174
	v_lshlrev_b32_e32 v140, 16, v175
	v_and_b32_e32 v141, 0xffff0000, v175
	v_lshlrev_b32_e32 v142, 16, v176
	v_and_b32_e32 v143, 0xffff0000, v176
	v_lshlrev_b32_e32 v144, 16, v177
	v_and_b32_e32 v145, 0xffff0000, v177
	v_pk_mul_f32 v[194:195], v[130:131], v[2:3]
	v_pk_mul_f32 v[196:197], v[130:131], v[18:19]
	v_pk_mul_f32 v[198:199], v[130:131], v[34:35]
	v_pk_mul_f32 v[200:201], v[130:131], v[50:51]
	v_pk_mul_f32 v[202:203], v[130:131], v[66:67]
	v_pk_mul_f32 v[204:205], v[130:131], v[82:83]
	v_pk_mul_f32 v[206:207], v[130:131], v[98:99]
	v_pk_mul_f32 v[182:183], v[130:131], v[114:115]
	v_pk_fma_f32 v[194:195], v[132:133], v[4:5], v[194:195]
	v_pk_fma_f32 v[196:197], v[132:133], v[20:21], v[196:197]
	v_pk_fma_f32 v[198:199], v[132:133], v[36:37], v[198:199]
	v_pk_fma_f32 v[200:201], v[132:133], v[52:53], v[200:201]
	v_pk_fma_f32 v[202:203], v[132:133], v[68:69], v[202:203]
	v_pk_fma_f32 v[204:205], v[132:133], v[84:85], v[204:205]
	v_pk_fma_f32 v[206:207], v[132:133], v[100:101], v[206:207]
	v_pk_fma_f32 v[182:183], v[132:133], v[116:117], v[182:183]
	v_pk_fma_f32 v[194:195], v[134:135], v[6:7], v[194:195]
	v_pk_fma_f32 v[196:197], v[134:135], v[22:23], v[196:197]
	v_pk_fma_f32 v[198:199], v[134:135], v[38:39], v[198:199]
	v_pk_fma_f32 v[200:201], v[134:135], v[54:55], v[200:201]
	v_pk_fma_f32 v[202:203], v[134:135], v[70:71], v[202:203]
	v_pk_fma_f32 v[204:205], v[134:135], v[86:87], v[204:205]
	v_pk_fma_f32 v[206:207], v[134:135], v[102:103], v[206:207]
	v_pk_fma_f32 v[182:183], v[134:135], v[118:119], v[182:183]
	v_pk_fma_f32 v[194:195], v[136:137], v[8:9], v[194:195]
	v_pk_fma_f32 v[196:197], v[136:137], v[24:25], v[196:197]
	v_pk_fma_f32 v[198:199], v[136:137], v[40:41], v[198:199]
	v_pk_fma_f32 v[200:201], v[136:137], v[56:57], v[200:201]
	v_pk_fma_f32 v[202:203], v[136:137], v[72:73], v[202:203]
	v_pk_fma_f32 v[204:205], v[136:137], v[88:89], v[204:205]
	v_pk_fma_f32 v[206:207], v[136:137], v[104:105], v[206:207]
	v_pk_fma_f32 v[182:183], v[136:137], v[120:121], v[182:183]
	v_pk_fma_f32 v[194:195], v[138:139], v[10:11], v[194:195]
	v_pk_fma_f32 v[196:197], v[138:139], v[26:27], v[196:197]
	v_pk_fma_f32 v[198:199], v[138:139], v[42:43], v[198:199]
	v_pk_fma_f32 v[200:201], v[138:139], v[58:59], v[200:201]
	v_pk_fma_f32 v[202:203], v[138:139], v[74:75], v[202:203]
	v_pk_fma_f32 v[204:205], v[138:139], v[90:91], v[204:205]
	v_pk_fma_f32 v[206:207], v[138:139], v[106:107], v[206:207]
	v_pk_fma_f32 v[182:183], v[138:139], v[122:123], v[182:183]
	v_pk_fma_f32 v[194:195], v[140:141], v[12:13], v[194:195]
	v_pk_fma_f32 v[196:197], v[140:141], v[28:29], v[196:197]
	v_pk_fma_f32 v[198:199], v[140:141], v[44:45], v[198:199]
	v_pk_fma_f32 v[200:201], v[140:141], v[60:61], v[200:201]
	v_pk_fma_f32 v[202:203], v[140:141], v[76:77], v[202:203]
	v_pk_fma_f32 v[204:205], v[140:141], v[92:93], v[204:205]
	v_pk_fma_f32 v[206:207], v[140:141], v[108:109], v[206:207]
	v_pk_fma_f32 v[182:183], v[140:141], v[124:125], v[182:183]
	v_pk_fma_f32 v[194:195], v[142:143], v[14:15], v[194:195]
	v_pk_fma_f32 v[196:197], v[142:143], v[30:31], v[196:197]
	v_pk_fma_f32 v[198:199], v[142:143], v[46:47], v[198:199]
	v_pk_fma_f32 v[200:201], v[142:143], v[62:63], v[200:201]
	v_pk_fma_f32 v[202:203], v[142:143], v[78:79], v[202:203]
	v_pk_fma_f32 v[204:205], v[142:143], v[94:95], v[204:205]
	v_pk_fma_f32 v[206:207], v[142:143], v[110:111], v[206:207]
	v_pk_fma_f32 v[182:183], v[142:143], v[126:127], v[182:183]
	v_pk_fma_f32 v[194:195], v[144:145], v[16:17], v[194:195]
	v_pk_fma_f32 v[196:197], v[144:145], v[32:33], v[196:197]
	v_pk_fma_f32 v[198:199], v[144:145], v[48:49], v[198:199]
	v_pk_fma_f32 v[200:201], v[144:145], v[64:65], v[200:201]
	v_pk_fma_f32 v[202:203], v[144:145], v[80:81], v[202:203]
	v_pk_fma_f32 v[204:205], v[144:145], v[96:97], v[204:205]
	v_pk_fma_f32 v[206:207], v[144:145], v[112:113], v[206:207]
	v_pk_fma_f32 v[182:183], v[144:145], v[128:129], v[182:183]
	v_add_f32_e32 v194, v194, v195
	v_add_f32_e32 v196, v196, v197
	v_add_f32_e32 v198, v198, v199
	v_add_f32_e32 v200, v200, v201
	v_add_f32_e32 v202, v202, v203
	v_add_f32_e32 v204, v204, v205
	v_add_f32_e32 v206, v206, v207
	v_add_f32_e32 v182, v182, v183
	s_nop 1
	v_permlane32_swap_b32_e32 v194, v202
	v_permlane32_swap_b32_e32 v196, v204
	v_permlane32_swap_b32_e32 v198, v206
	v_permlane32_swap_b32_e32 v200, v182
	v_add_f32_e32 v194, v194, v202
	v_add_f32_e32 v196, v196, v204
	v_add_f32_e32 v198, v198, v206
	v_add_f32_e32 v200, v200, v182
	s_nop 1
	v_permlane16_swap_b32_e32 v194, v198
	v_permlane16_swap_b32_e32 v196, v200
	v_add_f32_e32 v194, v194, v198
	v_add_f32_e32 v196, v196, v200
	s_nop 1
	v_add_f32_dpp v240, v194, v194 row_ror:8 row_mask:0xf bank_mask:0x3
	v_add_f32_dpp v240, v196, v196 row_ror:8 row_mask:0xf bank_mask:0xc
	s_nop 1
	v_add_f32_dpp v241, v233, v233 row_half_mirror row_mask:0xf bank_mask:0x5
	v_add_f32_dpp v241, v237, v237 row_half_mirror row_mask:0xf bank_mask:0xa
	v_add_f32_dpp v242, v234, v234 row_half_mirror row_mask:0xf bank_mask:0x5
	v_add_f32_dpp v242, v238, v238 row_half_mirror row_mask:0xf bank_mask:0xa
	v_add_f32_dpp v243, v235, v235 row_half_mirror row_mask:0xf bank_mask:0x5
	v_add_f32_dpp v243, v239, v239 row_half_mirror row_mask:0xf bank_mask:0xa
	v_add_f32_dpp v244, v236, v236 row_half_mirror row_mask:0xf bank_mask:0x5
; __device__ __forceinline__ void fg_tail(const Args& a, int l, LAS unsigned char* lds, const int tid) {
;     ...
;     for (int chunk = blockIdx.x * 8 + wid; chunk * 8 < MT; chunk += gridDim.x * 8) {
;         const int rowc = chunk * 8, b = rowc >> 11;
;         f32x4 sh[4];
; #pragma unroll
;         for (int q = 0; q < 4; ++q) sh[q] = *(const f32x4*)(mod + (size_t)b * MODW + 16 * lane + 4 * q);
; #pragma unroll 1
;         for (int jb = 0; jb < 8; jb += 4) {
;             f32x4 rs4v[4]; u32x4 w0v[4], w1v[4];
; #pragma unroll
;             for (int j = 0; j < 4; ++j) { const int row = rowc + jb + j; rs4v[j] = *(const f32x4*)(rowss + (size_t)row * 4); w0v[j] = *(const u32x4*)(H + (size_t)row * DM + 16 * lane); w1v[j] = *(const u32x4*)(H + (size_t)row * DM + 16 * lane + 8); }
; #pragma unroll
;             for (int j = 0; j < 4; ++j) {
;                 const int row = rowc + jb + j;
;                 const f32x4 rs4 = rs4v[j]; const u32x4 w0 = w0v[j], w1 = w1v[j];
;                 const float r = 1.0f / sqrtf(((rs4[0] + rs4[1]) + (rs4[2] + rs4[3])) * (1.0f / 1024.0f) + EPS);
;                 float h[16];
; #pragma unroll
;                 for (int i = 0; i < 4; ++i) { h[2 * i] = __uint_as_float(w0[i] << 16); h[2 * i + 1] = __uint_as_float(w0[i] & 0xffff0000u); h[8 + 2 * i] = __uint_as_float(w1[i] << 16); h[8 + 2 * i + 1] = __uint_as_float(w1[i] & 0xffff0000u); }
; #pragma unroll
;                 for (int q = 0; q < 4; ++q) { h[4 * q] = h[4 * q] * r + sh[q][0]; h[4 * q + 1] = h[4 * q + 1] * r + sh[q][1]; h[4 * q + 2] = h[4 * q + 2] * r + sh[q][2]; h[4 * q + 3] = h[4 * q + 3] * r + sh[q][3]; }
;                 float d8[8];
; #pragma unroll
;                 for (int j8 = 0; j8 < 8; ++j8) { float acc = 0.f;
; #pragma unroll
;                     for (int q = 0; q < 4; ++q) { const f32x4 w = wl[(j8 * 4 + q) * 64 + lane]; acc += (h[4 * q] * w[0] + h[4 * q + 1] * w[1]) + (h[4 * q + 2] * w[2] + h[4 * q + 3] * w[3]); }
;                     d8[j8] = acc; }
;                 const float tot = reduce8(d8, lane);
;                 if ((lane & 7) == 0) { const float z = tot + bfv; logf[(size_t)row * 8 + (lane >> 3)] = fminf(z, 0.f) - log1pf(__expf(-fabsf(z))); }
	v_add_f32_dpp v244, v240, v240 row_half_mirror row_mask:0xf bank_mask:0xa
	v_cndmask_b32_e64 v235, v243, v241, s[30:31]
	v_cndmask_b32_e64 v237, v241, v243, s[30:31]
	v_cndmask_b32_e64 v236, v244, v242, s[30:31]
	v_cndmask_b32_e64 v238, v242, v244, s[30:31]
	s_nop 1
	v_add_f32_dpp v233, v235, v237 quad_perm:[2,3,0,1] row_mask:0xf bank_mask:0xf
	v_add_f32_dpp v234, v236, v238 quad_perm:[2,3,0,1] row_mask:0xf bank_mask:0xf
	v_cndmask_b32_e64 v239, v234, v233, s[40:41]
	v_cndmask_b32_e64 v240, v233, v234, s[40:41]
	s_nop 1
	v_add_f32_dpp v245, v239, v240 quad_perm:[1,0,3,2] row_mask:0xf bank_mask:0xf
	v_fma_f32 v182, v247, v245, v248
	v_mul_f32_e64 v183, |v182|, s26
	v_exp_f32_e32 v183, v183
	v_min_f32_e32 v182, 0, v182
	v_add_f32_e32 v184, 1.0, v183
	v_add_f32_e32 v185, -1.0, v184
	v_sub_f32_e32 v216, v185, v184
	v_sub_f32_e32 v185, v183, v185
	v_add_f32_e32 v216, 1.0, v216
	v_frexp_mant_f32_e32 v187, v184
	v_add_f32_e32 v185, v185, v216
	v_cvt_f64_f32_e32 v[216:217], v184
	v_frexp_exp_i32_f64_e32 v216, v[216:217]
	v_cmp_gt_f32_e32 vcc, s17, v187
	s_nop 1
	v_subbrev_co_u32_e32 v218, vcc, 0, v216, vcc
	v_sub_u32_e32 v187, 0, v218
	v_ldexp_f32 v184, v184, v187
	v_ldexp_f32 v185, v185, v187
	v_add_f32_e32 v187, -1.0, v184
	v_add_f32_e32 v217, 1.0, v184
	v_add_f32_e32 v216, 1.0, v187
	v_add_f32_e32 v228, -1.0, v217
	v_sub_f32_e32 v216, v184, v216
	v_sub_f32_e32 v184, v184, v228
	v_add_f32_e32 v184, v185, v184
	v_add_f32_e32 v216, v185, v216
	v_add_f32_e32 v185, v217, v184
	v_rcp_f32_e32 v228, v185
	v_sub_f32_e32 v217, v185, v217
	v_sub_f32_e32 v184, v184, v217
	v_add_f32_e32 v217, v187, v216
	v_mul_f32_e32 v233, v217, v228
	v_mul_f32_e32 v234, v185, v233
	v_fma_f32 v236, v233, v185, -v234
	v_sub_f32_e32 v187, v217, v187
	v_fmac_f32_e32 v236, v233, v184
	v_sub_f32_e32 v187, v216, v187
	v_add_f32_e32 v216, v234, v236
	v_sub_f32_e32 v235, v217, v216
	v_pk_add_f32 v[238:239], v[216:217], v[234:235] neg_lo:[0,1] neg_hi:[0,1]
	v_mov_b32_e32 v237, v216
	v_pk_add_f32 v[216:217], v[238:239], v[236:237] neg_lo:[0,1] neg_hi:[0,1]
	v_cmp_neq_f32_e32 vcc, s43, v183
	v_add_f32_e32 v187, v187, v217
	v_add_f32_e32 v187, v216, v187
	v_add_f32_e32 v217, v235, v187
	v_mul_f32_e32 v240, v228, v217
	v_mul_f32_e32 v234, v185, v240
	v_fma_f32 v236, v240, v185, -v234
	v_fmac_f32_e32 v236, v240, v184
	v_add_f32_e32 v216, v234, v236
	v_sub_f32_e32 v184, v235, v217
	v_sub_f32_e32 v235, v217, v216
	v_pk_add_f32 v[238:239], v[216:217], v[234:235] neg_lo:[0,1] neg_hi:[0,1]
	v_mov_b32_e32 v237, v216
	v_add_f32_e32 v184, v187, v184
	v_pk_add_f32 v[216:217], v[238:239], v[236:237] neg_lo:[0,1] neg_hi:[0,1]
	v_add_f32_e32 v185, v233, v240
	v_add_f32_e32 v184, v184, v217
	v_add_f32_e32 v184, v216, v184
	v_add_f32_e32 v184, v235, v184
	v_sub_f32_e32 v187, v185, v233
	v_mul_f32_e32 v184, v228, v184
	v_sub_f32_e32 v187, v240, v187
	v_add_f32_e32 v184, v187, v184
	v_add_f32_e32 v217, v185, v184
	v_cvt_f32_i32_e32 v216, v218
	v_mul_f32_e32 v228, v217, v217
	v_fmamk_f32 v187, v228, 0x3e9b6dac, v227
	v_fmaak_f32 v187, v228, v187, 0x3f2aaada
	v_sub_f32_e32 v185, v217, v185
	v_ldexp_f32 v235, v217, 1
	v_mul_f32_e32 v217, v217, v228
	v_pk_mul_f32 v[236:237], v[216:217], v[186:187]
	v_sub_f32_e32 v184, v184, v185
	v_fma_f32 v234, v216, s18, -v236
	v_fmac_f32_e32 v234, 0xb102e308, v216
	v_pk_add_f32 v[216:217], v[236:237], v[234:235]
	v_ldexp_f32 v184, v184, 1
	v_sub_f32_e32 v185, v217, v235
	v_sub_f32_e32 v185, v237, v185
	v_add_f32_e32 v239, v184, v185
	v_mov_b32_e32 v238, v236
	v_pk_add_f32 v[236:237], v[216:217], v[236:237] neg_lo:[0,1] neg_hi:[0,1]
	v_pk_add_f32 v[240:241], v[216:217], v[238:239]
	v_mov_b32_e32 v235, v216
	v_mov_b32_e32 v237, v241
	v_pk_add_f32 v[242:243], v[234:235], v[236:237] neg_lo:[0,1] neg_hi:[0,1]
	v_pk_add_f32 v[234:235], v[234:235], v[236:237]
	v_mov_b32_e32 v238, v239
	v_pk_add_f32 v[236:237], v[234:235], v[216:217] op_sel:[1,0] op_sel_hi:[0,1] neg_lo:[0,1] neg_hi:[0,1]
	v_pk_add_f32 v[244:245], v[240:241], v[236:237] op_sel_hi:[1,0] neg_lo:[0,1] neg_hi:[0,1]
	v_mov_b32_e32 v240, v241
	v_mov_b32_e32 v241, v235
	v_pk_mov_b32 v[236:237], v[216:217], v[236:237] op_sel:[1,0]
	v_mov_b32_e32 v239, v216
	v_pk_add_f32 v[236:237], v[240:241], v[236:237] neg_lo:[0,1] neg_hi:[0,1]
	v_mov_b32_e32 v244, v242
	v_pk_add_f32 v[216:217], v[238:239], v[236:237] neg_lo:[0,1] neg_hi:[0,1]
	v_mov_b32_e32 v243, v235
	v_pk_add_f32 v[236:237], v[244:245], v[216:217]
	s_nop 0
	v_pk_add_f32 v[238:239], v[236:237], v[236:237] op_sel:[0,1] op_sel_hi:[1,0]
	s_nop 0
	v_pk_add_f32 v[234:235], v[234:235], v[238:239] op_sel:[1,0] op_sel_hi:[0,1]
	v_mov_b32_e32 v237, v234
	v_pk_add_f32 v[240:241], v[236:237], v[242:243] neg_lo:[0,1] neg_hi:[0,1]
	v_mov_b32_e32 v217, v238
	v_sub_f32_e32 v184, v236, v240
	v_pk_add_f32 v[216:217], v[216:217], v[240:241] neg_lo:[0,1] neg_hi:[0,1]
	v_sub_f32_e32 v184, v242, v184
	v_add_f32_e32 v184, v216, v184
	v_add_f32_e32 v184, v184, v217
	v_add_f32_e32 v184, v234, v184
	v_cndmask_b32_e32 v184, v229, v184, vcc
	v_cmp_ngt_f32_e32 vcc, -1.0, v183
	s_nop 1
	v_cndmask_b32_e32 v184, v231, v184, vcc
	v_cmp_neq_f32_e32 vcc, -1.0, v183
	s_nop 1
	v_cndmask_b32_e32 v184, v232, v184, vcc
	v_cmp_lt_f32_e64 vcc, |v183|, s19
	s_nop 1
	v_cndmask_b32_e32 v183, v184, v183, vcc
	v_sub_f32_e32 v182, v182, v183
	global_store_dword v246, v182, s[4:5]
	v_add_u32_e32 v0, s92, v0
	s_nop 0
	v_readfirstlane_b32 s52, v0
	s_cmp_le_i32 s52, s83
	s_cbranch_scc0 .Lfg_exit
	v_lshlrev_b32_e32 v184, 14, v0
	v_lshl_add_u32 v184, v208, 5, v184
	v_lshrrev_b32_e32 v215, 8, v0
	v_mul_u32_u24_e32 v215, 0x6000, v215
	v_lshl_add_u32 v215, v208, 6, v215
	v_and_b32_e32 v216, 7, v208
	v_lshlrev_b32_e32 v217, 7, v0
	v_lshl_add_u32 v217, v216, 4, v217
	v_lshlrev_b32_e32 v246, 8, v0
	v_lshl_add_u32 v246, v216, 5, v246
	v_lshrrev_b32_e32 v216, 3, v208
	v_lshl_add_u32 v246, v216, 2, v246
	global_load_dwordx4 v[130:133], v215, s[2:3]
	global_load_dwordx4 v[134:137], v215, s[2:3] offset:16
	global_load_dwordx4 v[138:141], v215, s[2:3] offset:32
	global_load_dwordx4 v[142:145], v215, s[2:3] offset:48
	global_load_dwordx4 v[178:181], v217, s[34:35]
	global_load_dwordx4 v[146:149], v184, s[94:95]
	global_load_dwordx4 v[150:153], v184, s[94:95] offset:16
	global_load_dwordx4 v[154:157], v184, s[94:95] offset:2048
	global_load_dwordx4 v[158:161], v184, s[94:95] offset:2064
	v_add_u32_e32 v184, 0x1000, v184
	global_load_dwordx4 v[162:165], v184, s[94:95]
	global_load_dwordx4 v[166:169], v184, s[94:95] offset:16
	global_load_dwordx4 v[170:173], v184, s[94:95] offset:2048
	global_load_dwordx4 v[174:177], v184, s[94:95] offset:2064
	v_add_u32_e32 v184, 0x1000, v184
	s_branch .Lfg_loop
; __device__ __forceinline__ void fg_tail(const Args& a, int l, LAS unsigned char* lds, const int tid) {
;     ...
;     {
;         const f32x4* wsrc = (const f32x4*)((const float*)(ws + WS_WFGT) + (size_t)l * 8192);
; #pragma unroll
;         for (int i = 0; i < 4; ++i) { const int idx = tid + 512 * i, j = idx >> 8, k4 = idx & 255, ln = k4 >> 2, q = k4 & 3; wl[(j * 4 + q) * 64 + ln] = wsrc[idx]; }
;     }
;     __syncthreads();
;     const bf16_t* H = (const bf16_t*)(ws + WS_H); const float* rowss = (const float*)(ws + WS_ROWSS) + (size_t)(2 * l) * MT * 4;
;     const float* mod = (const float*)(ws + WS_MOD) + (size_t)l * 8 * MODW; float* logf = (float*)(ws + WS_LOGF);
;     const float bfv = a.in[7][l * 8 + (lane >> 3)];
;     for (int chunk = blockIdx.x * 8 + wid; chunk * 8 < MT; chunk += gridDim.x * 8) {
; __global__ void __launch_bounds__(512, 2) fwd_kernel(Args a) {
;     ...
;                 fg_tail(a, l, lds, tidv); if (a.probe & 1024) fg_tail(a, l, lds, tidv); }
.Lfg_exit:
.LBB0_493:
	s_or_b64 exec, exec, s[38:39]
	s_mov_b64 s[2:3], 0x2000
	v_lshl_add_u64 v[6:7], v[190:191], 0, s[2:3]
	s_mov_b64 s[2:3], 0x4000
	v_lshl_add_u64 v[4:5], v[190:191], 0, s[2:3]
	s_mov_b64 s[2:3], 0x6000
	v_lshl_add_u64 v[2:3], v[190:191], 0, s[2:3]
	v_readlane_b32 s2, v250, 3
	v_readlane_b32 s3, v250, 4
	v_readlane_b32 s60, v251, 40
	s_andn2_b64 vcc, exec, s[2:3]
	v_readlane_b32 s61, v251, 41
	v_readlane_b32 s62, v251, 42
	v_readlane_b32 s63, v251, 43
	v_readlane_b32 s64, v251, 44
	v_readlane_b32 s65, v251, 45
	v_readlane_b32 s66, v251, 46
	v_readlane_b32 s67, v251, 47
	v_readlane_b32 s70, v251, 50
	v_readlane_b32 s71, v251, 51
	v_readlane_b32 s72, v251, 52
	v_readlane_b32 s73, v251, 53
	v_readlane_b32 s74, v251, 54
	v_readlane_b32 s75, v251, 55
	v_mov_b32_e32 v248, v212
	v_mov_b64_e32 v[246:247], 0x100
	s_waitcnt lgkmcnt(0)
	s_barrier
	v_readlane_b32 s68, v251, 48
	v_readlane_b32 s69, v251, 49
	s_cbranch_vccnz .LBB0_508
	global_load_dwordx4 v[8:11], v[190:191], off
	s_waitcnt vmcnt(0)
	ds_write_b128 v209, v[8:11]
	global_load_dwordx4 v[6:9], v[6:7], off
	s_waitcnt vmcnt(0)
	ds_write_b128 v210, v[6:9]
	global_load_dwordx4 v[4:7], v[4:5], off
	s_waitcnt vmcnt(0)
	ds_write_b128 v211, v[4:7]
	global_load_dwordx4 v[2:5], v[2:3], off
	s_waitcnt vmcnt(0)
	ds_write_b128 v213, v[2:5]
	s_waitcnt lgkmcnt(0)
	s_barrier
	s_and_saveexec_b64 s[10:11], s[0:1]
	s_cbranch_execz .LBB0_507
	global_load_dword v204, v[192:193], off
	v_readlane_b32 s0, v252, 32
	v_lshlrev_b32_e32 v0, 6, v208
	v_readlane_b32 s1, v252, 33
	v_and_b32_e32 v2, 16, v188
	v_cmp_eq_u32_e64 s[2:3], 0, v2
	v_lshl_add_u64 v[190:191], s[0:1], 0, v[0:1]
	v_lshlrev_b32_e32 v0, 5, v208
	v_lshl_add_u64 v[192:193], s[94:95], 0, v[0:1]
	v_lshl_add_u32 v0, v208, 4, 0
	v_and_b32_e32 v2, 8, v188
	v_cmp_eq_u32_e64 s[4:5], 0, v2
	ds_read_b128 v[2:5], v0
	ds_read_b128 v[6:9], v0 offset:1024
	ds_read_b128 v[10:13], v0 offset:2048
	ds_read_b128 v[14:17], v0 offset:3072
	ds_read_b128 v[18:21], v0 offset:4096
	ds_read_b128 v[22:25], v0 offset:5120
	ds_read_b128 v[26:29], v0 offset:6144
	ds_read_b128 v[30:33], v0 offset:7168
	ds_read_b128 v[34:37], v0 offset:8192
	ds_read_b128 v[38:41], v0 offset:9216
	ds_read_b128 v[42:45], v0 offset:10240
	ds_read_b128 v[46:49], v0 offset:11264
	ds_read_b128 v[50:53], v0 offset:12288
	ds_read_b128 v[54:57], v0 offset:13312
	ds_read_b128 v[58:61], v0 offset:14336
	ds_read_b128 v[62:65], v0 offset:15360
	ds_read_b128 v[66:69], v0 offset:16384
	ds_read_b128 v[70:73], v0 offset:17408
	ds_read_b128 v[74:77], v0 offset:18432
	ds_read_b128 v[78:81], v0 offset:19456
	ds_read_b128 v[82:85], v0 offset:20480
	ds_read_b128 v[86:89], v0 offset:21504
	ds_read_b128 v[90:93], v0 offset:22528
	ds_read_b128 v[94:97], v0 offset:23552
	ds_read_b128 v[98:101], v0 offset:24576
	ds_read_b128 v[102:105], v0 offset:25600
	ds_read_b128 v[106:109], v0 offset:26624
	ds_read_b128 v[110:113], v0 offset:27648
	ds_read_b128 v[114:117], v0 offset:28672
	ds_read_b128 v[118:121], v0 offset:29696
	ds_read_b128 v[122:125], v0 offset:30720
	ds_read_b128 v[126:129], v0 offset:31744
	v_bfe_u32 v0, v188, 3, 3
	v_readlane_b32 s8, v249, 61
	v_and_b32_e32 v130, 7, v188
	v_lshlrev_b32_e32 v0, 2, v0
	v_readlane_b32 s9, v249, 62
	v_cmp_gt_u32_e64 s[0:1], 32, v208
	v_cmp_eq_u32_e64 s[6:7], 0, v130
	v_lshl_add_u64 v[194:195], s[8:9], 0, v[0:1]
	s_mov_b64 s[38:39], 0
	s_branch .LBB0_497
